# k10_resid
# speedup vs baseline: 1.0961x; 1.0348x over previous
; DI f32x16 mfma32(bf16x8 a, bf16x8 b, f32x16 c) { return __builtin_amdgcn_mfma_f32_32x32x16_bf16(a, b, c, 0, 0, 0); }
; template <int NT, class Epi>
; DI void gemm_tile(const u16* __restrict__ A, int lda, const u16* __restrict__ Bt, int ldb, int K, int m0, int n0, const Epi& epi, char* smem) {
;     ...
;   for (int kt = 0; kt < nk; ++kt) {
; #pragma unroll
;     for (int i = 0; i < 4; ++i) *(u32x4*)(As + (lrow + 32 * i) * 72 + lch * 8) = ra[i];
; #pragma unroll
;     for (int i = 0; i < NB8; ++i) *(u32x4*)(Bs + (lrow + 32 * i) * 72 + lch * 8) = rb[i];
;     __syncthreads();
;     if (kt + 1 < nk) {
;       const int k0 = (kt + 1) * 64;
; #pragma unroll
;       for (int i = 0; i < 4; ++i) ra[i] = *(const u32x4*)(Ap + (size_t)(32 * i) * lda + k0);
; #pragma unroll
;       for (int i = 0; i < NB8; ++i) rb[i] = *(const u32x4*)(Bp + (size_t)(32 * i) * ldb + k0);
;     }
; #pragma unroll
;     for (int ks = 0; ks < 4; ++ks) {
;       bf16x8 a[2], b[NT];
; #pragma unroll
;       for (int mt = 0; mt < 2; ++mt) a[mt] = *(const bf16x8*)(As + (wm * 64 + mt * 32 + r) * 72 + ks * 16 + h * 8);
; #pragma unroll
;       for (int nt = 0; nt < NT; ++nt) b[nt] = *(const bf16x8*)(Bs + (wn * 32 * NT + nt * 32 + r) * 72 + ks * 16 + h * 8);
; #pragma unroll
;       for (int mt = 0; mt < 2; ++mt)
; #pragma unroll
;         for (int nt = 0; nt < NT; ++nt) acc[mt][nt] = mfma32(a[mt], b[nt], acc[mt][nt]);
;     }
.LBB0_422:
	s_waitcnt vmcnt(11)
	ds_write_b128 v206, v[128:131]
	s_waitcnt vmcnt(10)
	ds_write_b128 v206, v[132:135] offset:4608
	s_waitcnt vmcnt(9)
	ds_write_b128 v206, v[136:139] offset:9216
	s_waitcnt vmcnt(8)
	ds_write_b128 v206, v[140:143] offset:13824
	s_waitcnt vmcnt(7)
	ds_write_b128 v206, v[144:147] offset:18432
	s_waitcnt vmcnt(6)
	ds_write_b128 v206, v[148:151] offset:23040
	s_waitcnt vmcnt(5)
	ds_write_b128 v206, v[152:155] offset:27648
	s_waitcnt vmcnt(4)
	ds_write_b128 v206, v[156:159] offset:32256
	s_waitcnt vmcnt(3)
	ds_write_b128 v206, v[160:163] offset:36864
	s_waitcnt vmcnt(2)
	ds_write_b128 v206, v[164:167] offset:41472
	s_waitcnt vmcnt(1)
	ds_write_b128 v206, v[168:171] offset:46080
	s_waitcnt vmcnt(0)
	ds_write_b128 v206, v[172:175] offset:50688
	s_waitcnt lgkmcnt(0)
	s_barrier
	ds_read_b128 v[128:131], v207
	ds_read_b128 v[132:135], v208 offset:18432
	ds_read_b128 v[136:139], v207 offset:32
	ds_read_b128 v[140:143], v208 offset:18464
	ds_read_b128 v[144:147], v208 offset:23040
	ds_read_b128 v[148:151], v208 offset:23072
	ds_read_b128 v[152:155], v208 offset:27648
	ds_read_b128 v[156:159], v208 offset:27680
	ds_read_b128 v[160:163], v208 offset:32256
	ds_read_b128 v[164:167], v208 offset:32288
	s_waitcnt lgkmcnt(8)
	v_mfma_f32_32x32x16_bf16 v[112:127], v[128:131], v[132:135], v[112:127]
	s_waitcnt lgkmcnt(5)
	v_mfma_f32_32x32x16_bf16 v[96:111], v[128:131], v[144:147], v[96:111]
	s_waitcnt lgkmcnt(3)
	v_mfma_f32_32x32x16_bf16 v[80:95], v[128:131], v[152:155], v[80:95]
	s_waitcnt lgkmcnt(1)
	v_mfma_f32_32x32x16_bf16 v[64:79], v[128:131], v[160:163], v[64:79]
	ds_read_b128 v[128:131], v207 offset:4608
	ds_read_b128 v[168:171], v207 offset:4640
	s_waitcnt lgkmcnt(1)
	v_mfma_f32_32x32x16_bf16 v[48:63], v[128:131], v[132:135], v[48:63]
	v_mfma_f32_32x32x16_bf16 v[32:47], v[128:131], v[144:147], v[32:47]
	v_mfma_f32_32x32x16_bf16 v[16:31], v[128:131], v[152:155], v[16:31]
	v_mfma_f32_32x32x16_bf16 v[112:127], v[136:139], v[140:143], v[112:127]
	v_mfma_f32_32x32x16_bf16 v[96:111], v[136:139], v[148:151], v[96:111]
	v_mfma_f32_32x32x16_bf16 v[80:95], v[136:139], v[156:159], v[80:95]
	v_mfma_f32_32x32x16_bf16 v[64:79], v[136:139], v[164:167], v[64:79]
	v_mfma_f32_32x32x16_bf16 v[0:15], v[128:131], v[160:163], v[0:15]
	s_waitcnt lgkmcnt(0)
	v_mfma_f32_32x32x16_bf16 v[48:63], v[168:171], v[140:143], v[48:63]
	ds_read_b128 v[128:131], v207 offset:64
	ds_read_b128 v[132:135], v208 offset:18496
	ds_read_b128 v[136:139], v207 offset:96
	ds_read_b128 v[140:143], v208 offset:18528
	v_mfma_f32_32x32x16_bf16 v[32:47], v[168:171], v[148:151], v[32:47]
	ds_read_b128 v[144:147], v208 offset:23104
	ds_read_b128 v[148:151], v208 offset:23136
	ds_read_b128 v[152:155], v208 offset:27712
	ds_read_b128 v[172:175], v208 offset:27744
	v_mfma_f32_32x32x16_bf16 v[16:31], v[168:171], v[156:159], v[16:31]
	ds_read_b128 v[156:159], v208 offset:32320
	ds_read_b128 v[210:213], v208 offset:32352
	s_waitcnt lgkmcnt(8)
	v_mfma_f32_32x32x16_bf16 v[112:127], v[128:131], v[132:135], v[112:127]
	s_waitcnt lgkmcnt(5)
	v_mfma_f32_32x32x16_bf16 v[96:111], v[128:131], v[144:147], v[96:111]
	s_waitcnt lgkmcnt(3)
	v_mfma_f32_32x32x16_bf16 v[80:95], v[128:131], v[152:155], v[80:95]
	s_waitcnt lgkmcnt(1)
	v_mfma_f32_32x32x16_bf16 v[64:79], v[128:131], v[156:159], v[64:79]
	ds_read_b128 v[128:131], v207 offset:4672
	ds_read_b128 v[222:225], v207 offset:4704
	s_waitcnt lgkmcnt(1)
	v_mfma_f32_32x32x16_bf16 v[48:63], v[128:131], v[132:135], v[48:63]
	v_lshl_add_u64 v[132:133], v[202:203], 0, s[16:17]
	v_lshl_add_u64 v[134:135], v[204:205], 0, s[16:17]
	s_add_u32 s16, s16, 0x80
	s_addc_u32 s17, s17, 0
	s_cmpk_lg_i32 s16, 0x780
	v_mfma_f32_32x32x16_bf16 v[0:15], v[168:171], v[164:167], v[0:15]
	v_mfma_f32_32x32x16_bf16 v[32:47], v[128:131], v[144:147], v[32:47]
	v_add_co_u32_e32 v144, vcc, s30, v132
	s_nop 1
	v_addc_co_u32_e32 v145, vcc, 0, v133, vcc
	v_add_co_u32_e32 v146, vcc, s31, v132
	v_mfma_f32_32x32x16_bf16 v[16:31], v[128:131], v[152:155], v[16:31]
	s_nop 0
	v_addc_co_u32_e32 v147, vcc, 0, v133, vcc
	v_add_co_u32_e32 v152, vcc, s34, v132
	s_nop 1
	v_addc_co_u32_e32 v153, vcc, 0, v133, vcc
	v_add_co_u32_e32 v154, vcc, s35, v132
	v_mfma_f32_32x32x16_bf16 v[0:15], v[128:131], v[156:159], v[0:15]
	s_nop 0
	v_addc_co_u32_e32 v155, vcc, 0, v133, vcc
	v_add_co_u32_e32 v156, vcc, s38, v134
	s_nop 1
	v_addc_co_u32_e32 v157, vcc, 0, v135, vcc
	v_add_co_u32_e32 v158, vcc, s39, v134
	v_mfma_f32_32x32x16_bf16 v[112:127], v[136:139], v[140:143], v[112:127]
	s_nop 0
	v_addc_co_u32_e32 v159, vcc, 0, v135, vcc
	v_add_co_u32_e32 v160, vcc, s40, v134
	s_nop 1
	v_addc_co_u32_e32 v161, vcc, 0, v135, vcc
	v_add_co_u32_e32 v162, vcc, s41, v134
	v_mfma_f32_32x32x16_bf16 v[96:111], v[136:139], v[148:151], v[96:111]
	s_nop 0
	v_addc_co_u32_e32 v163, vcc, 0, v135, vcc
	v_add_co_u32_e32 v164, vcc, s42, v134
	s_nop 1
	v_addc_co_u32_e32 v165, vcc, 0, v135, vcc
	v_add_co_u32_e32 v166, vcc, s43, v134
	v_mfma_f32_32x32x16_bf16 v[80:95], v[136:139], v[172:175], v[80:95]
	s_nop 0
	v_addc_co_u32_e32 v167, vcc, 0, v135, vcc
	v_add_co_u32_e32 v168, vcc, s44, v134
	s_nop 1
	v_addc_co_u32_e32 v169, vcc, 0, v135, vcc
	v_add_co_u32_e32 v214, vcc, s45, v134
	v_mfma_f32_32x32x16_bf16 v[64:79], v[136:139], v[210:213], v[64:79]
	s_nop 0
	v_addc_co_u32_e32 v215, vcc, 0, v135, vcc
	s_waitcnt lgkmcnt(0)
	v_mfma_f32_32x32x16_bf16 v[48:63], v[222:225], v[140:143], v[48:63]
	global_load_dwordx4 v[128:131], v[144:145], off offset:128
	global_load_dwordx4 v[132:135], v[146:147], off offset:128
	global_load_dwordx4 v[136:139], v[152:153], off offset:128
	global_load_dwordx4 v[140:143], v[154:155], off offset:128
	v_mfma_f32_32x32x16_bf16 v[32:47], v[222:225], v[148:151], v[32:47]
	global_load_dwordx4 v[144:147], v[156:157], off offset:128
	global_load_dwordx4 v[148:151], v[158:159], off offset:128
	global_load_dwordx4 v[152:155], v[160:161], off offset:128
	s_nop 0
	global_load_dwordx4 v[156:159], v[162:163], off offset:128
	s_nop 0
	global_load_dwordx4 v[160:163], v[164:165], off offset:128
	s_nop 0
	global_load_dwordx4 v[164:167], v[166:167], off offset:128
	s_nop 0
	global_load_dwordx4 v[168:171], v[168:169], off offset:128
	v_mfma_f32_32x32x16_bf16 v[16:31], v[222:225], v[172:175], v[16:31]
	global_load_dwordx4 v[172:175], v[214:215], off offset:128
	s_barrier
; DI int crow(int i, int h) { return (i & 3) + 8 * (i >> 2) + 4 * h; }
; DI f32x16 mfma32(bf16x8 a, bf16x8 b, f32x16 c) { return __builtin_amdgcn_mfma_f32_32x32x16_bf16(a, b, c, 0, 0, 0); }
; template <int NT, class Epi>
; DI void gemm_tile(const u16* __restrict__ A, int lda, const u16* __restrict__ Bt, int ldb, int K, int m0, int n0, const Epi& epi, char* smem) {
;     ...
; #pragma unroll
;     for (int ks = 0; ks < 4; ++ks) {
;       bf16x8 a[2], b[NT];
; #pragma unroll
;       for (int mt = 0; mt < 2; ++mt) a[mt] = *(const bf16x8*)(As + (wm * 64 + mt * 32 + r) * 72 + ks * 16 + h * 8);
; #pragma unroll
;       for (int nt = 0; nt < NT; ++nt) b[nt] = *(const bf16x8*)(Bs + (wn * 32 * NT + nt * 32 + r) * 72 + ks * 16 + h * 8);
; #pragma unroll
;       for (int mt = 0; mt < 2; ++mt)
; #pragma unroll
;         for (int nt = 0; nt < NT; ++nt) acc[mt][nt] = mfma32(a[mt], b[nt], acc[mt][nt]);
;     }
;     __syncthreads();
;   DI void operator()(const f32x16& acc, int row0, int col0, int lane) const {
;     const int r = lane & 31, h = lane >> 5, col = col0 + r;
; #pragma unroll
;     for (int i = 0; i < 16; ++i) { float* q = H + (size_t)(row0 + crow(i, h)) * DM + col; *q = *q + acc[i]; }
;   }
	v_mfma_f32_32x32x16_bf16 v[0:15], v[222:225], v[210:213], v[0:15]
	s_cbranch_scc1 .LBB0_422
	s_waitcnt vmcnt(11)
	ds_write_b128 v206, v[128:131]
	s_waitcnt vmcnt(10)
	ds_write_b128 v206, v[132:135] offset:4608
	s_waitcnt vmcnt(9)
	ds_write_b128 v206, v[136:139] offset:9216
	s_waitcnt vmcnt(8)
	ds_write_b128 v206, v[140:143] offset:13824
	s_waitcnt vmcnt(7)
	ds_write_b128 v206, v[144:147] offset:18432
	s_waitcnt vmcnt(6)
	ds_write_b128 v206, v[148:151] offset:23040
	s_waitcnt vmcnt(5)
	ds_write_b128 v206, v[152:155] offset:27648
	s_waitcnt vmcnt(4)
	ds_write_b128 v206, v[156:159] offset:32256
	s_waitcnt vmcnt(3)
	ds_write_b128 v206, v[160:163] offset:36864
	s_waitcnt vmcnt(2)
	ds_write_b128 v206, v[164:167] offset:41472
	s_waitcnt vmcnt(1)
	ds_write_b128 v206, v[168:171] offset:46080
	s_waitcnt vmcnt(0)
	ds_write_b128 v206, v[172:175] offset:50688
	s_waitcnt lgkmcnt(0)
	s_barrier
	ds_read_b128 v[128:131], v207 offset:4608
	ds_read_b128 v[132:135], v208 offset:23040
	ds_read_b128 v[136:139], v208 offset:27648
	ds_read_b128 v[140:143], v208 offset:32256
	ds_read_b128 v[144:147], v207
	ds_read_b128 v[148:151], v207 offset:32
	ds_read_b128 v[152:155], v208 offset:18432
	ds_read_b128 v[156:159], v208 offset:18464
	s_waitcnt lgkmcnt(1)
	v_mfma_f32_32x32x16_bf16 v[112:127], v[144:147], v[152:155], v[112:127]
	v_add_lshl_u32 v192, v181, s59, 12
	s_add_i32 s58, s58, s78
	s_add_i32 s18, s18, s19
	s_cmpk_lt_u32 s58, 0x100
	v_mfma_f32_32x32x16_bf16 v[96:111], v[144:147], v[132:135], v[96:111]
	v_mfma_f32_32x32x16_bf16 v[80:95], v[144:147], v[136:139], v[80:95]
	v_mfma_f32_32x32x16_bf16 v[64:79], v[144:147], v[140:143], v[64:79]
	v_mfma_f32_32x32x16_bf16 v[48:63], v[128:131], v[152:155], v[48:63]
	v_or_b32_e32 v154, 0x3000, v192
	v_mov_b32_e32 v155, v193
	v_or_b32_e32 v152, 0x8000, v192
	v_mov_b32_e32 v153, v193
	v_mfma_f32_32x32x16_bf16 v[32:47], v[128:131], v[132:135], v[32:47]
	v_mfma_f32_32x32x16_bf16 v[16:31], v[128:131], v[136:139], v[16:31]
	v_mfma_f32_32x32x16_bf16 v[0:15], v[128:131], v[140:143], v[0:15]
	ds_read_b128 v[128:131], v207 offset:4640
	ds_read_b128 v[132:135], v208 offset:23072
	ds_read_b128 v[136:139], v208 offset:27680
	ds_read_b128 v[140:143], v208 offset:32288
	s_waitcnt lgkmcnt(4)
	v_mfma_f32_32x32x16_bf16 v[112:127], v[148:151], v[156:159], v[112:127]
	s_waitcnt lgkmcnt(2)
	v_mfma_f32_32x32x16_bf16 v[96:111], v[148:151], v[132:135], v[96:111]
	s_waitcnt lgkmcnt(1)
	v_mfma_f32_32x32x16_bf16 v[80:95], v[148:151], v[136:139], v[80:95]
	s_waitcnt lgkmcnt(0)
	v_mfma_f32_32x32x16_bf16 v[64:79], v[148:151], v[140:143], v[64:79]
	v_mfma_f32_32x32x16_bf16 v[48:63], v[128:131], v[156:159], v[48:63]
	v_or_b32_e32 v158, 0x1000, v192
	v_mov_b32_e32 v159, v193
	v_or_b32_e32 v156, 0x2000, v192
	v_mov_b32_e32 v157, v193
	v_mfma_f32_32x32x16_bf16 v[32:47], v[128:131], v[132:135], v[32:47]
	v_mfma_f32_32x32x16_bf16 v[16:31], v[128:131], v[136:139], v[16:31]
	v_mfma_f32_32x32x16_bf16 v[0:15], v[128:131], v[140:143], v[0:15]
	ds_read_b128 v[128:131], v207 offset:64
	ds_read_b128 v[132:135], v207 offset:4672
	ds_read_b128 v[136:139], v208 offset:18496
	ds_read_b128 v[140:143], v208 offset:23104
	ds_read_b128 v[144:147], v208 offset:27712
	ds_read_b128 v[148:151], v208 offset:32320
	s_waitcnt lgkmcnt(3)
	v_mfma_f32_32x32x16_bf16 v[112:127], v[128:131], v[136:139], v[112:127]
	s_waitcnt lgkmcnt(2)
	v_mfma_f32_32x32x16_bf16 v[96:111], v[128:131], v[140:143], v[96:111]
	s_waitcnt lgkmcnt(1)
	v_mfma_f32_32x32x16_bf16 v[80:95], v[128:131], v[144:147], v[80:95]
	s_waitcnt lgkmcnt(0)
	v_mfma_f32_32x32x16_bf16 v[64:79], v[128:131], v[148:151], v[64:79]
	v_mfma_f32_32x32x16_bf16 v[48:63], v[132:135], v[136:139], v[48:63]
	v_mfma_f32_32x32x16_bf16 v[32:47], v[132:135], v[140:143], v[32:47]
	v_mfma_f32_32x32x16_bf16 v[16:31], v[132:135], v[144:147], v[16:31]
	v_mfma_f32_32x32x16_bf16 v[0:15], v[132:135], v[148:151], v[0:15]
	ds_read_b128 v[128:131], v207 offset:96
	ds_read_b128 v[132:135], v207 offset:4704
	ds_read_b128 v[136:139], v208 offset:18528
	ds_read_b128 v[140:143], v208 offset:23136
	ds_read_b128 v[144:147], v208 offset:27744
	ds_read_b128 v[148:151], v208 offset:32352
	s_waitcnt lgkmcnt(0)
	s_barrier
	v_mfma_f32_32x32x16_bf16 v[112:127], v[128:131], v[136:139], v[112:127]
	v_mfma_f32_32x32x16_bf16 v[96:111], v[128:131], v[140:143], v[96:111]
	v_mfma_f32_32x32x16_bf16 v[80:95], v[128:131], v[144:147], v[80:95]
	v_mfma_f32_32x32x16_bf16 v[64:79], v[128:131], v[148:151], v[64:79]
	v_mfma_f32_32x32x16_bf16 v[0:15], v[132:135], v[148:151], v[0:15]
	v_mfma_f32_32x32x16_bf16 v[16:31], v[132:135], v[144:147], v[16:31]
	v_mfma_f32_32x32x16_bf16 v[32:47], v[132:135], v[140:143], v[32:47]
	v_mfma_f32_32x32x16_bf16 v[48:63], v[132:135], v[136:139], v[48:63]
	s_cselect_b32 s91, 1, 0
	v_or_b32_e32 v239, s60, v179
	v_lshlrev_b32_e32 v239, 2, v239
	v_add_u32_e32 v239, v239, v192
	s_add_u32 s92, s68, 0x0
	s_addc_u32 s93, s69, 0
	global_load_dword v128, v239, s[92:93]
	s_add_u32 s92, s68, 0x1000
	s_addc_u32 s93, s69, 0
	global_load_dword v129, v239, s[92:93]
	s_add_u32 s92, s68, 0x2000
	s_addc_u32 s93, s69, 0
	global_load_dword v130, v239, s[92:93]
	s_add_u32 s92, s68, 0x3000
	s_addc_u32 s93, s69, 0
	global_load_dword v131, v239, s[92:93]
	s_add_u32 s92, s68, 0x8000
	s_addc_u32 s93, s69, 0
	global_load_dword v132, v239, s[92:93]
	s_add_u32 s92, s68, 0x9000
	s_addc_u32 s93, s69, 0
	global_load_dword v133, v239, s[92:93]
	s_add_u32 s92, s68, 0xa000
	s_addc_u32 s93, s69, 0
	global_load_dword v134, v239, s[92:93]
	s_add_u32 s92, s68, 0xb000
	s_addc_u32 s93, s69, 0
	global_load_dword v135, v239, s[92:93]
	s_add_u32 s92, s68, 0x10000
	s_addc_u32 s93, s69, 0
; DI int crow(int i, int h) { return (i & 3) + 8 * (i >> 2) + 4 * h; }
; template <int NT, class Epi>
; DI void gemm_tile(const u16* __restrict__ A, int lda, const u16* __restrict__ Bt, int ldb, int K, int m0, int n0, const Epi& epi, char* smem) {
;     ...
; #pragma unroll
;   for (int mt = 0; mt < 2; ++mt)
; #pragma unroll
;     for (int nt = 0; nt < NT; ++nt) epi(acc[mt][nt], m0 + wm * 64 + mt * 32, n0 + wn * 32 * NT + nt * 32, lane);
;   DI void operator()(const f32x16& acc, int row0, int col0, int lane) const {
;     const int r = lane & 31, h = lane >> 5, col = col0 + r;
; #pragma unroll
;     for (int i = 0; i < 16; ++i) { float* q = H + (size_t)(row0 + crow(i, h)) * DM + col; *q = *q + acc[i]; }
;   }
	global_load_dword v136, v239, s[92:93]
	s_add_u32 s92, s68, 0x11000
	s_addc_u32 s93, s69, 0
	global_load_dword v137, v239, s[92:93]
	s_add_u32 s92, s68, 0x12000
	s_addc_u32 s93, s69, 0
	global_load_dword v138, v239, s[92:93]
	s_add_u32 s92, s68, 0x13000
	s_addc_u32 s93, s69, 0
	global_load_dword v139, v239, s[92:93]
	s_add_u32 s92, s68, 0x18000
	s_addc_u32 s93, s69, 0
	global_load_dword v140, v239, s[92:93]
	s_add_u32 s92, s68, 0x19000
	s_addc_u32 s93, s69, 0
	global_load_dword v141, v239, s[92:93]
	s_add_u32 s92, s68, 0x1a000
	s_addc_u32 s93, s69, 0
	global_load_dword v142, v239, s[92:93]
	s_add_u32 s92, s68, 0x1b000
	s_addc_u32 s93, s69, 0
	global_load_dword v143, v239, s[92:93]
	s_add_u32 s92, s68, 0x80
	s_addc_u32 s93, s69, 0
	global_load_dword v240, v239, s[92:93]
	s_add_u32 s92, s68, 0x1080
	s_addc_u32 s93, s69, 0
	global_load_dword v241, v239, s[92:93]
	s_add_u32 s92, s68, 0x2080
	s_addc_u32 s93, s69, 0
	global_load_dword v242, v239, s[92:93]
	s_add_u32 s92, s68, 0x3080
	s_addc_u32 s93, s69, 0
	global_load_dword v243, v239, s[92:93]
	s_add_u32 s92, s68, 0x8080
	s_addc_u32 s93, s69, 0
	global_load_dword v244, v239, s[92:93]
	s_add_u32 s92, s68, 0x9080
	s_addc_u32 s93, s69, 0
	global_load_dword v245, v239, s[92:93]
	s_add_u32 s92, s68, 0xa080
	s_addc_u32 s93, s69, 0
	global_load_dword v246, v239, s[92:93]
	s_add_u32 s92, s68, 0xb080
	s_addc_u32 s93, s69, 0
	global_load_dword v247, v239, s[92:93]
	s_add_u32 s92, s68, 0x10080
	s_addc_u32 s93, s69, 0
	global_load_dword v248, v239, s[92:93]
	s_add_u32 s92, s68, 0x11080
	s_addc_u32 s93, s69, 0
	global_load_dword v249, v239, s[92:93]
	s_add_u32 s92, s68, 0x12080
	s_addc_u32 s93, s69, 0
	global_load_dword v250, v239, s[92:93]
	s_add_u32 s92, s68, 0x13080
	s_addc_u32 s93, s69, 0
	global_load_dword v251, v239, s[92:93]
	s_add_u32 s92, s68, 0x18080
	s_addc_u32 s93, s69, 0
	global_load_dword v252, v239, s[92:93]
	s_add_u32 s92, s68, 0x19080
	s_addc_u32 s93, s69, 0
	global_load_dword v253, v239, s[92:93]
	s_add_u32 s92, s68, 0x1a080
	s_addc_u32 s93, s69, 0
	global_load_dword v254, v239, s[92:93]
	s_add_u32 s92, s68, 0x1b080
	s_addc_u32 s93, s69, 0
	global_load_dword v255, v239, s[92:93]
	s_waitcnt vmcnt(16)
	v_add_f32_e32 v112, v112, v128
	v_add_f32_e32 v113, v113, v129
	v_add_f32_e32 v114, v114, v130
	v_add_f32_e32 v115, v115, v131
	v_add_f32_e32 v116, v116, v132
	v_add_f32_e32 v117, v117, v133
	v_add_f32_e32 v118, v118, v134
	v_add_f32_e32 v119, v119, v135
	v_add_f32_e32 v120, v120, v136
	v_add_f32_e32 v121, v121, v137
	v_add_f32_e32 v122, v122, v138
	v_add_f32_e32 v123, v123, v139
	v_add_f32_e32 v124, v124, v140
	v_add_f32_e32 v125, v125, v141
	v_add_f32_e32 v126, v126, v142
	v_add_f32_e32 v127, v127, v143
	s_add_u32 s92, s68, 0x0
	s_addc_u32 s93, s69, 0
	global_store_dword v239, v112, s[92:93]
	s_add_u32 s92, s68, 0x1000
	s_addc_u32 s93, s69, 0
	global_store_dword v239, v113, s[92:93]
	s_add_u32 s92, s68, 0x2000
	s_addc_u32 s93, s69, 0
	global_store_dword v239, v114, s[92:93]
	s_add_u32 s92, s68, 0x3000
	s_addc_u32 s93, s69, 0
	global_store_dword v239, v115, s[92:93]
	s_add_u32 s92, s68, 0x8000
	s_addc_u32 s93, s69, 0
	global_store_dword v239, v116, s[92:93]
	s_add_u32 s92, s68, 0x9000
	s_addc_u32 s93, s69, 0
	global_store_dword v239, v117, s[92:93]
	s_add_u32 s92, s68, 0xa000
	s_addc_u32 s93, s69, 0
	global_store_dword v239, v118, s[92:93]
	s_add_u32 s92, s68, 0xb000
	s_addc_u32 s93, s69, 0
	global_store_dword v239, v119, s[92:93]
	s_add_u32 s92, s68, 0x10000
	s_addc_u32 s93, s69, 0
	global_store_dword v239, v120, s[92:93]
	s_add_u32 s92, s68, 0x11000
	s_addc_u32 s93, s69, 0
	global_store_dword v239, v121, s[92:93]
	s_add_u32 s92, s68, 0x12000
	s_addc_u32 s93, s69, 0
	global_store_dword v239, v122, s[92:93]
	s_add_u32 s92, s68, 0x13000
	s_addc_u32 s93, s69, 0
	global_store_dword v239, v123, s[92:93]
	s_add_u32 s92, s68, 0x18000
	s_addc_u32 s93, s69, 0
	global_store_dword v239, v124, s[92:93]
	s_add_u32 s92, s68, 0x19000
	s_addc_u32 s93, s69, 0
	global_store_dword v239, v125, s[92:93]
	s_add_u32 s92, s68, 0x1a000
	s_addc_u32 s93, s69, 0
	global_store_dword v239, v126, s[92:93]
	s_add_u32 s92, s68, 0x1b000
	s_addc_u32 s93, s69, 0
	global_store_dword v239, v127, s[92:93]
	s_add_u32 s92, s68, 0x100
	s_addc_u32 s93, s69, 0
	global_load_dword v128, v239, s[92:93]
	s_add_u32 s92, s68, 0x1100
	s_addc_u32 s93, s69, 0
	global_load_dword v129, v239, s[92:93]
	s_add_u32 s92, s68, 0x2100
	s_addc_u32 s93, s69, 0
	global_load_dword v130, v239, s[92:93]
	s_add_u32 s92, s68, 0x3100
	s_addc_u32 s93, s69, 0
	global_load_dword v131, v239, s[92:93]
	s_add_u32 s92, s68, 0x8100
	s_addc_u32 s93, s69, 0
	global_load_dword v132, v239, s[92:93]
	s_add_u32 s92, s68, 0x9100
	s_addc_u32 s93, s69, 0
	global_load_dword v133, v239, s[92:93]
	s_add_u32 s92, s68, 0xa100
	s_addc_u32 s93, s69, 0
	global_load_dword v134, v239, s[92:93]
	s_add_u32 s92, s68, 0xb100
	s_addc_u32 s93, s69, 0
	global_load_dword v135, v239, s[92:93]
	s_add_u32 s92, s68, 0x10100
	s_addc_u32 s93, s69, 0
	global_load_dword v136, v239, s[92:93]
	s_add_u32 s92, s68, 0x11100
	s_addc_u32 s93, s69, 0
	global_load_dword v137, v239, s[92:93]
	s_add_u32 s92, s68, 0x12100
	s_addc_u32 s93, s69, 0
	global_load_dword v138, v239, s[92:93]
	s_add_u32 s92, s68, 0x13100
	s_addc_u32 s93, s69, 0
	global_load_dword v139, v239, s[92:93]
	s_add_u32 s92, s68, 0x18100
	s_addc_u32 s93, s69, 0
	global_load_dword v140, v239, s[92:93]
	s_add_u32 s92, s68, 0x19100
	s_addc_u32 s93, s69, 0
	global_load_dword v141, v239, s[92:93]
	s_add_u32 s92, s68, 0x1a100
	s_addc_u32 s93, s69, 0
	global_load_dword v142, v239, s[92:93]
	s_add_u32 s92, s68, 0x1b100
	s_addc_u32 s93, s69, 0
	global_load_dword v143, v239, s[92:93]
	s_waitcnt vmcnt(32)
; DI int crow(int i, int h) { return (i & 3) + 8 * (i >> 2) + 4 * h; }
; template <int NT, class Epi>
; DI void gemm_tile(const u16* __restrict__ A, int lda, const u16* __restrict__ Bt, int ldb, int K, int m0, int n0, const Epi& epi, char* smem) {
;     ...
; #pragma unroll
;   for (int mt = 0; mt < 2; ++mt)
; #pragma unroll
;     for (int nt = 0; nt < NT; ++nt) epi(acc[mt][nt], m0 + wm * 64 + mt * 32, n0 + wn * 32 * NT + nt * 32, lane);
;   DI void operator()(const f32x16& acc, int row0, int col0, int lane) const {
;     const int r = lane & 31, h = lane >> 5, col = col0 + r;
; #pragma unroll
;     for (int i = 0; i < 16; ++i) { float* q = H + (size_t)(row0 + crow(i, h)) * DM + col; *q = *q + acc[i]; }
;   }
	v_add_f32_e32 v96, v96, v240
	v_add_f32_e32 v97, v97, v241
	v_add_f32_e32 v98, v98, v242
	v_add_f32_e32 v99, v99, v243
	v_add_f32_e32 v100, v100, v244
	v_add_f32_e32 v101, v101, v245
	v_add_f32_e32 v102, v102, v246
	v_add_f32_e32 v103, v103, v247
	v_add_f32_e32 v104, v104, v248
	v_add_f32_e32 v105, v105, v249
	v_add_f32_e32 v106, v106, v250
	v_add_f32_e32 v107, v107, v251
	v_add_f32_e32 v108, v108, v252
	v_add_f32_e32 v109, v109, v253
	v_add_f32_e32 v110, v110, v254
	v_add_f32_e32 v111, v111, v255
	s_add_u32 s92, s68, 0x80
	s_addc_u32 s93, s69, 0
	global_store_dword v239, v96, s[92:93]
	s_add_u32 s92, s68, 0x1080
	s_addc_u32 s93, s69, 0
	global_store_dword v239, v97, s[92:93]
	s_add_u32 s92, s68, 0x2080
	s_addc_u32 s93, s69, 0
	global_store_dword v239, v98, s[92:93]
	s_add_u32 s92, s68, 0x3080
	s_addc_u32 s93, s69, 0
	global_store_dword v239, v99, s[92:93]
	s_add_u32 s92, s68, 0x8080
	s_addc_u32 s93, s69, 0
	global_store_dword v239, v100, s[92:93]
	s_add_u32 s92, s68, 0x9080
	s_addc_u32 s93, s69, 0
	global_store_dword v239, v101, s[92:93]
	s_add_u32 s92, s68, 0xa080
	s_addc_u32 s93, s69, 0
	global_store_dword v239, v102, s[92:93]
	s_add_u32 s92, s68, 0xb080
	s_addc_u32 s93, s69, 0
	global_store_dword v239, v103, s[92:93]
	s_add_u32 s92, s68, 0x10080
	s_addc_u32 s93, s69, 0
	global_store_dword v239, v104, s[92:93]
	s_add_u32 s92, s68, 0x11080
	s_addc_u32 s93, s69, 0
	global_store_dword v239, v105, s[92:93]
	s_add_u32 s92, s68, 0x12080
	s_addc_u32 s93, s69, 0
	global_store_dword v239, v106, s[92:93]
	s_add_u32 s92, s68, 0x13080
	s_addc_u32 s93, s69, 0
	global_store_dword v239, v107, s[92:93]
	s_add_u32 s92, s68, 0x18080
	s_addc_u32 s93, s69, 0
	global_store_dword v239, v108, s[92:93]
	s_add_u32 s92, s68, 0x19080
	s_addc_u32 s93, s69, 0
	global_store_dword v239, v109, s[92:93]
	s_add_u32 s92, s68, 0x1a080
	s_addc_u32 s93, s69, 0
	global_store_dword v239, v110, s[92:93]
	s_add_u32 s92, s68, 0x1b080
	s_addc_u32 s93, s69, 0
	global_store_dword v239, v111, s[92:93]
	s_add_u32 s92, s68, 0x180
	s_addc_u32 s93, s69, 0
	global_load_dword v240, v239, s[92:93]
	s_add_u32 s92, s68, 0x1180
	s_addc_u32 s93, s69, 0
	global_load_dword v241, v239, s[92:93]
	s_add_u32 s92, s68, 0x2180
	s_addc_u32 s93, s69, 0
	global_load_dword v242, v239, s[92:93]
	s_add_u32 s92, s68, 0x3180
	s_addc_u32 s93, s69, 0
	global_load_dword v243, v239, s[92:93]
	s_add_u32 s92, s68, 0x8180
	s_addc_u32 s93, s69, 0
	global_load_dword v244, v239, s[92:93]
	s_add_u32 s92, s68, 0x9180
	s_addc_u32 s93, s69, 0
	global_load_dword v245, v239, s[92:93]
	s_add_u32 s92, s68, 0xa180
	s_addc_u32 s93, s69, 0
	global_load_dword v246, v239, s[92:93]
	s_add_u32 s92, s68, 0xb180
	s_addc_u32 s93, s69, 0
	global_load_dword v247, v239, s[92:93]
	s_add_u32 s92, s68, 0x10180
	s_addc_u32 s93, s69, 0
	global_load_dword v248, v239, s[92:93]
	s_add_u32 s92, s68, 0x11180
	s_addc_u32 s93, s69, 0
	global_load_dword v249, v239, s[92:93]
	s_add_u32 s92, s68, 0x12180
	s_addc_u32 s93, s69, 0
	global_load_dword v250, v239, s[92:93]
	s_add_u32 s92, s68, 0x13180
	s_addc_u32 s93, s69, 0
	global_load_dword v251, v239, s[92:93]
	s_add_u32 s92, s68, 0x18180
	s_addc_u32 s93, s69, 0
	global_load_dword v252, v239, s[92:93]
	s_add_u32 s92, s68, 0x19180
	s_addc_u32 s93, s69, 0
	global_load_dword v253, v239, s[92:93]
	s_add_u32 s92, s68, 0x1a180
	s_addc_u32 s93, s69, 0
	global_load_dword v254, v239, s[92:93]
	s_add_u32 s92, s68, 0x1b180
	s_addc_u32 s93, s69, 0
	global_load_dword v255, v239, s[92:93]
	s_waitcnt vmcnt(32)
	v_add_f32_e32 v80, v80, v128
	v_add_f32_e32 v81, v81, v129
	v_add_f32_e32 v82, v82, v130
	v_add_f32_e32 v83, v83, v131
	v_add_f32_e32 v84, v84, v132
	v_add_f32_e32 v85, v85, v133
	v_add_f32_e32 v86, v86, v134
	v_add_f32_e32 v87, v87, v135
	v_add_f32_e32 v88, v88, v136
	v_add_f32_e32 v89, v89, v137
	v_add_f32_e32 v90, v90, v138
	v_add_f32_e32 v91, v91, v139
	v_add_f32_e32 v92, v92, v140
	v_add_f32_e32 v93, v93, v141
	v_add_f32_e32 v94, v94, v142
	v_add_f32_e32 v95, v95, v143
	s_add_u32 s92, s68, 0x100
	s_addc_u32 s93, s69, 0
	global_store_dword v239, v80, s[92:93]
	s_add_u32 s92, s68, 0x1100
	s_addc_u32 s93, s69, 0
	global_store_dword v239, v81, s[92:93]
	s_add_u32 s92, s68, 0x2100
	s_addc_u32 s93, s69, 0
	global_store_dword v239, v82, s[92:93]
	s_add_u32 s92, s68, 0x3100
	s_addc_u32 s93, s69, 0
	global_store_dword v239, v83, s[92:93]
	s_add_u32 s92, s68, 0x8100
	s_addc_u32 s93, s69, 0
	global_store_dword v239, v84, s[92:93]
	s_add_u32 s92, s68, 0x9100
	s_addc_u32 s93, s69, 0
	global_store_dword v239, v85, s[92:93]
	s_add_u32 s92, s68, 0xa100
	s_addc_u32 s93, s69, 0
	global_store_dword v239, v86, s[92:93]
	s_add_u32 s92, s68, 0xb100
	s_addc_u32 s93, s69, 0
	global_store_dword v239, v87, s[92:93]
	s_add_u32 s92, s68, 0x10100
	s_addc_u32 s93, s69, 0
	global_store_dword v239, v88, s[92:93]
	s_add_u32 s92, s68, 0x11100
	s_addc_u32 s93, s69, 0
	global_store_dword v239, v89, s[92:93]
	s_add_u32 s92, s68, 0x12100
	s_addc_u32 s93, s69, 0
	global_store_dword v239, v90, s[92:93]
	s_add_u32 s92, s68, 0x13100
	s_addc_u32 s93, s69, 0
	global_store_dword v239, v91, s[92:93]
	s_add_u32 s92, s68, 0x18100
	s_addc_u32 s93, s69, 0
	global_store_dword v239, v92, s[92:93]
	s_add_u32 s92, s68, 0x19100
	s_addc_u32 s93, s69, 0
	global_store_dword v239, v93, s[92:93]
	s_add_u32 s92, s68, 0x1a100
	s_addc_u32 s93, s69, 0
	global_store_dword v239, v94, s[92:93]
	s_add_u32 s92, s68, 0x1b100
	s_addc_u32 s93, s69, 0
	global_store_dword v239, v95, s[92:93]
	s_add_u32 s92, s68, 0x20000
	s_addc_u32 s93, s69, 0
	global_load_dword v128, v239, s[92:93]
	s_add_u32 s92, s68, 0x21000
	s_addc_u32 s93, s69, 0
	global_load_dword v129, v239, s[92:93]
	s_add_u32 s92, s68, 0x22000
	s_addc_u32 s93, s69, 0
	global_load_dword v130, v239, s[92:93]
	s_add_u32 s92, s68, 0x23000
	s_addc_u32 s93, s69, 0
	global_load_dword v131, v239, s[92:93]
	s_add_u32 s92, s68, 0x28000
	s_addc_u32 s93, s69, 0
	global_load_dword v132, v239, s[92:93]
	s_add_u32 s92, s68, 0x29000
	s_addc_u32 s93, s69, 0
	global_load_dword v133, v239, s[92:93]
	s_add_u32 s92, s68, 0x2a000
	s_addc_u32 s93, s69, 0
	global_load_dword v134, v239, s[92:93]
	s_add_u32 s92, s68, 0x2b000
	s_addc_u32 s93, s69, 0
	global_load_dword v135, v239, s[92:93]
	s_add_u32 s92, s68, 0x30000
	s_addc_u32 s93, s69, 0
	global_load_dword v136, v239, s[92:93]
	s_add_u32 s92, s68, 0x31000
	s_addc_u32 s93, s69, 0
	global_load_dword v137, v239, s[92:93]
	s_add_u32 s92, s68, 0x32000
	s_addc_u32 s93, s69, 0
	global_load_dword v138, v239, s[92:93]
	s_add_u32 s92, s68, 0x33000
	s_addc_u32 s93, s69, 0
	global_load_dword v139, v239, s[92:93]
	s_add_u32 s92, s68, 0x38000
	s_addc_u32 s93, s69, 0
	global_load_dword v140, v239, s[92:93]
	s_add_u32 s92, s68, 0x39000
	s_addc_u32 s93, s69, 0
	global_load_dword v141, v239, s[92:93]
	s_add_u32 s92, s68, 0x3a000
	s_addc_u32 s93, s69, 0
	global_load_dword v142, v239, s[92:93]
	s_add_u32 s92, s68, 0x3b000
	s_addc_u32 s93, s69, 0
	global_load_dword v143, v239, s[92:93]
	s_waitcnt vmcnt(32)
; DI int crow(int i, int h) { return (i & 3) + 8 * (i >> 2) + 4 * h; }
; template <int NT, class Epi>
; DI void gemm_tile(const u16* __restrict__ A, int lda, const u16* __restrict__ Bt, int ldb, int K, int m0, int n0, const Epi& epi, char* smem) {
;     ...
; #pragma unroll
;   for (int mt = 0; mt < 2; ++mt)
; #pragma unroll
;     for (int nt = 0; nt < NT; ++nt) epi(acc[mt][nt], m0 + wm * 64 + mt * 32, n0 + wn * 32 * NT + nt * 32, lane);
;   DI void operator()(const f32x16& acc, int row0, int col0, int lane) const {
;     const int r = lane & 31, h = lane >> 5, col = col0 + r;
; #pragma unroll
;     for (int i = 0; i < 16; ++i) { float* q = H + (size_t)(row0 + crow(i, h)) * DM + col; *q = *q + acc[i]; }
;   }
	v_add_f32_e32 v64, v64, v240
	v_add_f32_e32 v65, v65, v241
	v_add_f32_e32 v66, v66, v242
	v_add_f32_e32 v67, v67, v243
	v_add_f32_e32 v68, v68, v244
	v_add_f32_e32 v69, v69, v245
	v_add_f32_e32 v70, v70, v246
	v_add_f32_e32 v71, v71, v247
	v_add_f32_e32 v72, v72, v248
	v_add_f32_e32 v73, v73, v249
	v_add_f32_e32 v74, v74, v250
	v_add_f32_e32 v75, v75, v251
	v_add_f32_e32 v76, v76, v252
	v_add_f32_e32 v77, v77, v253
	v_add_f32_e32 v78, v78, v254
	v_add_f32_e32 v79, v79, v255
	s_add_u32 s92, s68, 0x180
	s_addc_u32 s93, s69, 0
	global_store_dword v239, v64, s[92:93]
	s_add_u32 s92, s68, 0x1180
	s_addc_u32 s93, s69, 0
	global_store_dword v239, v65, s[92:93]
	s_add_u32 s92, s68, 0x2180
	s_addc_u32 s93, s69, 0
	global_store_dword v239, v66, s[92:93]
	s_add_u32 s92, s68, 0x3180
	s_addc_u32 s93, s69, 0
	global_store_dword v239, v67, s[92:93]
	s_add_u32 s92, s68, 0x8180
	s_addc_u32 s93, s69, 0
	global_store_dword v239, v68, s[92:93]
	s_add_u32 s92, s68, 0x9180
	s_addc_u32 s93, s69, 0
	global_store_dword v239, v69, s[92:93]
	s_add_u32 s92, s68, 0xa180
	s_addc_u32 s93, s69, 0
	global_store_dword v239, v70, s[92:93]
	s_add_u32 s92, s68, 0xb180
	s_addc_u32 s93, s69, 0
	global_store_dword v239, v71, s[92:93]
	s_add_u32 s92, s68, 0x10180
	s_addc_u32 s93, s69, 0
	global_store_dword v239, v72, s[92:93]
	s_add_u32 s92, s68, 0x11180
	s_addc_u32 s93, s69, 0
	global_store_dword v239, v73, s[92:93]
	s_add_u32 s92, s68, 0x12180
	s_addc_u32 s93, s69, 0
	global_store_dword v239, v74, s[92:93]
	s_add_u32 s92, s68, 0x13180
	s_addc_u32 s93, s69, 0
	global_store_dword v239, v75, s[92:93]
	s_add_u32 s92, s68, 0x18180
	s_addc_u32 s93, s69, 0
	global_store_dword v239, v76, s[92:93]
	s_add_u32 s92, s68, 0x19180
	s_addc_u32 s93, s69, 0
	global_store_dword v239, v77, s[92:93]
	s_add_u32 s92, s68, 0x1a180
	s_addc_u32 s93, s69, 0
	global_store_dword v239, v78, s[92:93]
	s_add_u32 s92, s68, 0x1b180
	s_addc_u32 s93, s69, 0
	global_store_dword v239, v79, s[92:93]
	s_add_u32 s92, s68, 0x20080
	s_addc_u32 s93, s69, 0
	global_load_dword v240, v239, s[92:93]
	s_add_u32 s92, s68, 0x21080
	s_addc_u32 s93, s69, 0
	global_load_dword v241, v239, s[92:93]
	s_add_u32 s92, s68, 0x22080
	s_addc_u32 s93, s69, 0
	global_load_dword v242, v239, s[92:93]
	s_add_u32 s92, s68, 0x23080
	s_addc_u32 s93, s69, 0
	global_load_dword v243, v239, s[92:93]
	s_add_u32 s92, s68, 0x28080
	s_addc_u32 s93, s69, 0
	global_load_dword v244, v239, s[92:93]
	s_add_u32 s92, s68, 0x29080
	s_addc_u32 s93, s69, 0
	global_load_dword v245, v239, s[92:93]
	s_add_u32 s92, s68, 0x2a080
	s_addc_u32 s93, s69, 0
	global_load_dword v246, v239, s[92:93]
	s_add_u32 s92, s68, 0x2b080
	s_addc_u32 s93, s69, 0
	global_load_dword v247, v239, s[92:93]
	s_add_u32 s92, s68, 0x30080
	s_addc_u32 s93, s69, 0
	global_load_dword v248, v239, s[92:93]
	s_add_u32 s92, s68, 0x31080
	s_addc_u32 s93, s69, 0
	global_load_dword v249, v239, s[92:93]
	s_add_u32 s92, s68, 0x32080
	s_addc_u32 s93, s69, 0
	global_load_dword v250, v239, s[92:93]
	s_add_u32 s92, s68, 0x33080
	s_addc_u32 s93, s69, 0
	global_load_dword v251, v239, s[92:93]
	s_add_u32 s92, s68, 0x38080
	s_addc_u32 s93, s69, 0
	global_load_dword v252, v239, s[92:93]
	s_add_u32 s92, s68, 0x39080
	s_addc_u32 s93, s69, 0
	global_load_dword v253, v239, s[92:93]
	s_add_u32 s92, s68, 0x3a080
	s_addc_u32 s93, s69, 0
	global_load_dword v254, v239, s[92:93]
	s_add_u32 s92, s68, 0x3b080
	s_addc_u32 s93, s69, 0
	global_load_dword v255, v239, s[92:93]
	s_waitcnt vmcnt(32)
	v_add_f32_e32 v48, v48, v128
	v_add_f32_e32 v49, v49, v129
	v_add_f32_e32 v50, v50, v130
	v_add_f32_e32 v51, v51, v131
	v_add_f32_e32 v52, v52, v132
	v_add_f32_e32 v53, v53, v133
	v_add_f32_e32 v54, v54, v134
	v_add_f32_e32 v55, v55, v135
	v_add_f32_e32 v56, v56, v136
	v_add_f32_e32 v57, v57, v137
	v_add_f32_e32 v58, v58, v138
	v_add_f32_e32 v59, v59, v139
	v_add_f32_e32 v60, v60, v140
	v_add_f32_e32 v61, v61, v141
	v_add_f32_e32 v62, v62, v142
	v_add_f32_e32 v63, v63, v143
	s_add_u32 s92, s68, 0x20000
	s_addc_u32 s93, s69, 0
	global_store_dword v239, v48, s[92:93]
	s_add_u32 s92, s68, 0x21000
	s_addc_u32 s93, s69, 0
	global_store_dword v239, v49, s[92:93]
	s_add_u32 s92, s68, 0x22000
	s_addc_u32 s93, s69, 0
	global_store_dword v239, v50, s[92:93]
	s_add_u32 s92, s68, 0x23000
	s_addc_u32 s93, s69, 0
	global_store_dword v239, v51, s[92:93]
	s_add_u32 s92, s68, 0x28000
	s_addc_u32 s93, s69, 0
	global_store_dword v239, v52, s[92:93]
	s_add_u32 s92, s68, 0x29000
	s_addc_u32 s93, s69, 0
	global_store_dword v239, v53, s[92:93]
	s_add_u32 s92, s68, 0x2a000
	s_addc_u32 s93, s69, 0
	global_store_dword v239, v54, s[92:93]
	s_add_u32 s92, s68, 0x2b000
	s_addc_u32 s93, s69, 0
	global_store_dword v239, v55, s[92:93]
	s_add_u32 s92, s68, 0x30000
	s_addc_u32 s93, s69, 0
	global_store_dword v239, v56, s[92:93]
	s_add_u32 s92, s68, 0x31000
	s_addc_u32 s93, s69, 0
	global_store_dword v239, v57, s[92:93]
	s_add_u32 s92, s68, 0x32000
	s_addc_u32 s93, s69, 0
	global_store_dword v239, v58, s[92:93]
	s_add_u32 s92, s68, 0x33000
	s_addc_u32 s93, s69, 0
	global_store_dword v239, v59, s[92:93]
	s_add_u32 s92, s68, 0x38000
	s_addc_u32 s93, s69, 0
	global_store_dword v239, v60, s[92:93]
	s_add_u32 s92, s68, 0x39000
	s_addc_u32 s93, s69, 0
	global_store_dword v239, v61, s[92:93]
	s_add_u32 s92, s68, 0x3a000
	s_addc_u32 s93, s69, 0
	global_store_dword v239, v62, s[92:93]
	s_add_u32 s92, s68, 0x3b000
	s_addc_u32 s93, s69, 0
	global_store_dword v239, v63, s[92:93]
	s_add_u32 s92, s68, 0x20100
	s_addc_u32 s93, s69, 0
	global_load_dword v128, v239, s[92:93]
	s_add_u32 s92, s68, 0x21100
	s_addc_u32 s93, s69, 0
	global_load_dword v129, v239, s[92:93]
	s_add_u32 s92, s68, 0x22100
	s_addc_u32 s93, s69, 0
	global_load_dword v130, v239, s[92:93]
	s_add_u32 s92, s68, 0x23100
	s_addc_u32 s93, s69, 0
	global_load_dword v131, v239, s[92:93]
	s_add_u32 s92, s68, 0x28100
	s_addc_u32 s93, s69, 0
	global_load_dword v132, v239, s[92:93]
	s_add_u32 s92, s68, 0x29100
	s_addc_u32 s93, s69, 0
	global_load_dword v133, v239, s[92:93]
	s_add_u32 s92, s68, 0x2a100
	s_addc_u32 s93, s69, 0
	global_load_dword v134, v239, s[92:93]
	s_add_u32 s92, s68, 0x2b100
	s_addc_u32 s93, s69, 0
	global_load_dword v135, v239, s[92:93]
	s_add_u32 s92, s68, 0x30100
	s_addc_u32 s93, s69, 0
	global_load_dword v136, v239, s[92:93]
	s_add_u32 s92, s68, 0x31100
	s_addc_u32 s93, s69, 0
	global_load_dword v137, v239, s[92:93]
	s_add_u32 s92, s68, 0x32100
	s_addc_u32 s93, s69, 0
	global_load_dword v138, v239, s[92:93]
	s_add_u32 s92, s68, 0x33100
	s_addc_u32 s93, s69, 0
	global_load_dword v139, v239, s[92:93]
	s_add_u32 s92, s68, 0x38100
	s_addc_u32 s93, s69, 0
	global_load_dword v140, v239, s[92:93]
	s_add_u32 s92, s68, 0x39100
	s_addc_u32 s93, s69, 0
	global_load_dword v141, v239, s[92:93]
	s_add_u32 s92, s68, 0x3a100
	s_addc_u32 s93, s69, 0
	global_load_dword v142, v239, s[92:93]
	s_add_u32 s92, s68, 0x3b100
	s_addc_u32 s93, s69, 0
	global_load_dword v143, v239, s[92:93]
	s_waitcnt vmcnt(32)
; DI int crow(int i, int h) { return (i & 3) + 8 * (i >> 2) + 4 * h; }
; template <int NT, class Epi>
; DI void gemm_tile(const u16* __restrict__ A, int lda, const u16* __restrict__ Bt, int ldb, int K, int m0, int n0, const Epi& epi, char* smem) {
;     ...
; #pragma unroll
;   for (int mt = 0; mt < 2; ++mt)
; #pragma unroll
;     for (int nt = 0; nt < NT; ++nt) epi(acc[mt][nt], m0 + wm * 64 + mt * 32, n0 + wn * 32 * NT + nt * 32, lane);
;   DI void operator()(const f32x16& acc, int row0, int col0, int lane) const {
;     const int r = lane & 31, h = lane >> 5, col = col0 + r;
; #pragma unroll
;     for (int i = 0; i < 16; ++i) { float* q = H + (size_t)(row0 + crow(i, h)) * DM + col; *q = *q + acc[i]; }
;   }
	v_add_f32_e32 v32, v32, v240
	v_add_f32_e32 v33, v33, v241
	v_add_f32_e32 v34, v34, v242
	v_add_f32_e32 v35, v35, v243
	v_add_f32_e32 v36, v36, v244
	v_add_f32_e32 v37, v37, v245
	v_add_f32_e32 v38, v38, v246
	v_add_f32_e32 v39, v39, v247
	v_add_f32_e32 v40, v40, v248
	v_add_f32_e32 v41, v41, v249
	v_add_f32_e32 v42, v42, v250
	v_add_f32_e32 v43, v43, v251
	v_add_f32_e32 v44, v44, v252
	v_add_f32_e32 v45, v45, v253
	v_add_f32_e32 v46, v46, v254
	v_add_f32_e32 v47, v47, v255
	s_add_u32 s92, s68, 0x20080
	s_addc_u32 s93, s69, 0
	global_store_dword v239, v32, s[92:93]
	s_add_u32 s92, s68, 0x21080
	s_addc_u32 s93, s69, 0
	global_store_dword v239, v33, s[92:93]
	s_add_u32 s92, s68, 0x22080
	s_addc_u32 s93, s69, 0
	global_store_dword v239, v34, s[92:93]
	s_add_u32 s92, s68, 0x23080
	s_addc_u32 s93, s69, 0
	global_store_dword v239, v35, s[92:93]
	s_add_u32 s92, s68, 0x28080
	s_addc_u32 s93, s69, 0
	global_store_dword v239, v36, s[92:93]
	s_add_u32 s92, s68, 0x29080
	s_addc_u32 s93, s69, 0
	global_store_dword v239, v37, s[92:93]
	s_add_u32 s92, s68, 0x2a080
	s_addc_u32 s93, s69, 0
	global_store_dword v239, v38, s[92:93]
	s_add_u32 s92, s68, 0x2b080
	s_addc_u32 s93, s69, 0
	global_store_dword v239, v39, s[92:93]
	s_add_u32 s92, s68, 0x30080
	s_addc_u32 s93, s69, 0
	global_store_dword v239, v40, s[92:93]
	s_add_u32 s92, s68, 0x31080
	s_addc_u32 s93, s69, 0
	global_store_dword v239, v41, s[92:93]
	s_add_u32 s92, s68, 0x32080
	s_addc_u32 s93, s69, 0
	global_store_dword v239, v42, s[92:93]
	s_add_u32 s92, s68, 0x33080
	s_addc_u32 s93, s69, 0
	global_store_dword v239, v43, s[92:93]
	s_add_u32 s92, s68, 0x38080
	s_addc_u32 s93, s69, 0
	global_store_dword v239, v44, s[92:93]
	s_add_u32 s92, s68, 0x39080
	s_addc_u32 s93, s69, 0
	global_store_dword v239, v45, s[92:93]
	s_add_u32 s92, s68, 0x3a080
	s_addc_u32 s93, s69, 0
	global_store_dword v239, v46, s[92:93]
	s_add_u32 s92, s68, 0x3b080
	s_addc_u32 s93, s69, 0
	global_store_dword v239, v47, s[92:93]
	s_add_u32 s92, s68, 0x20180
	s_addc_u32 s93, s69, 0
	global_load_dword v240, v239, s[92:93]
	s_add_u32 s92, s68, 0x21180
	s_addc_u32 s93, s69, 0
	global_load_dword v241, v239, s[92:93]
	s_add_u32 s92, s68, 0x22180
	s_addc_u32 s93, s69, 0
	global_load_dword v242, v239, s[92:93]
	s_add_u32 s92, s68, 0x23180
	s_addc_u32 s93, s69, 0
	global_load_dword v243, v239, s[92:93]
	s_add_u32 s92, s68, 0x28180
	s_addc_u32 s93, s69, 0
	global_load_dword v244, v239, s[92:93]
	s_add_u32 s92, s68, 0x29180
	s_addc_u32 s93, s69, 0
	global_load_dword v245, v239, s[92:93]
	s_add_u32 s92, s68, 0x2a180
	s_addc_u32 s93, s69, 0
	global_load_dword v246, v239, s[92:93]
	s_add_u32 s92, s68, 0x2b180
	s_addc_u32 s93, s69, 0
	global_load_dword v247, v239, s[92:93]
	s_add_u32 s92, s68, 0x30180
	s_addc_u32 s93, s69, 0
	global_load_dword v248, v239, s[92:93]
	s_add_u32 s92, s68, 0x31180
	s_addc_u32 s93, s69, 0
	global_load_dword v249, v239, s[92:93]
	s_add_u32 s92, s68, 0x32180
	s_addc_u32 s93, s69, 0
	global_load_dword v250, v239, s[92:93]
	s_add_u32 s92, s68, 0x33180
	s_addc_u32 s93, s69, 0
	global_load_dword v251, v239, s[92:93]
	s_add_u32 s92, s68, 0x38180
	s_addc_u32 s93, s69, 0
	global_load_dword v252, v239, s[92:93]
	s_add_u32 s92, s68, 0x39180
	s_addc_u32 s93, s69, 0
	global_load_dword v253, v239, s[92:93]
	s_add_u32 s92, s68, 0x3a180
	s_addc_u32 s93, s69, 0
	global_load_dword v254, v239, s[92:93]
	s_add_u32 s92, s68, 0x3b180
	s_addc_u32 s93, s69, 0
	global_load_dword v255, v239, s[92:93]
	s_waitcnt vmcnt(32)
; DI int crow(int i, int h) { return (i & 3) + 8 * (i >> 2) + 4 * h; }
; template <int NT, class Epi>
; DI void gemm_tile(const u16* __restrict__ A, int lda, const u16* __restrict__ Bt, int ldb, int K, int m0, int n0, const Epi& epi, char* smem) {
;     ...
; #pragma unroll
;   for (int mt = 0; mt < 2; ++mt)
; #pragma unroll
;     for (int nt = 0; nt < NT; ++nt) epi(acc[mt][nt], m0 + wm * 64 + mt * 32, n0 + wn * 32 * NT + nt * 32, lane);
;   DI void operator()(const f32x16& acc, int row0, int col0, int lane) const {
;     const int r = lane & 31, h = lane >> 5, col = col0 + r;
; #pragma unroll
;     for (int i = 0; i < 16; ++i) { float* q = H + (size_t)(row0 + crow(i, h)) * DM + col; *q = *q + acc[i]; }
;   }
	v_add_f32_e32 v16, v16, v128
	v_add_f32_e32 v17, v17, v129
	v_add_f32_e32 v18, v18, v130
	v_add_f32_e32 v19, v19, v131
	v_add_f32_e32 v20, v20, v132
	v_add_f32_e32 v21, v21, v133
	v_add_f32_e32 v22, v22, v134
	v_add_f32_e32 v23, v23, v135
	v_add_f32_e32 v24, v24, v136
	v_add_f32_e32 v25, v25, v137
	v_add_f32_e32 v26, v26, v138
	v_add_f32_e32 v27, v27, v139
	v_add_f32_e32 v28, v28, v140
	v_add_f32_e32 v29, v29, v141
	v_add_f32_e32 v30, v30, v142
	v_add_f32_e32 v31, v31, v143
	s_add_u32 s92, s68, 0x20100
	s_addc_u32 s93, s69, 0
	global_store_dword v239, v16, s[92:93]
	s_add_u32 s92, s68, 0x21100
	s_addc_u32 s93, s69, 0
	global_store_dword v239, v17, s[92:93]
	s_add_u32 s92, s68, 0x22100
	s_addc_u32 s93, s69, 0
	global_store_dword v239, v18, s[92:93]
	s_add_u32 s92, s68, 0x23100
	s_addc_u32 s93, s69, 0
	global_store_dword v239, v19, s[92:93]
	s_add_u32 s92, s68, 0x28100
	s_addc_u32 s93, s69, 0
	global_store_dword v239, v20, s[92:93]
	s_add_u32 s92, s68, 0x29100
	s_addc_u32 s93, s69, 0
	global_store_dword v239, v21, s[92:93]
	s_add_u32 s92, s68, 0x2a100
	s_addc_u32 s93, s69, 0
	global_store_dword v239, v22, s[92:93]
	s_add_u32 s92, s68, 0x2b100
	s_addc_u32 s93, s69, 0
	global_store_dword v239, v23, s[92:93]
	s_add_u32 s92, s68, 0x30100
	s_addc_u32 s93, s69, 0
	global_store_dword v239, v24, s[92:93]
	s_add_u32 s92, s68, 0x31100
	s_addc_u32 s93, s69, 0
	global_store_dword v239, v25, s[92:93]
	s_add_u32 s92, s68, 0x32100
	s_addc_u32 s93, s69, 0
	global_store_dword v239, v26, s[92:93]
	s_add_u32 s92, s68, 0x33100
	s_addc_u32 s93, s69, 0
	global_store_dword v239, v27, s[92:93]
	s_add_u32 s92, s68, 0x38100
	s_addc_u32 s93, s69, 0
	global_store_dword v239, v28, s[92:93]
	s_add_u32 s92, s68, 0x39100
	s_addc_u32 s93, s69, 0
	global_store_dword v239, v29, s[92:93]
	s_add_u32 s92, s68, 0x3a100
	s_addc_u32 s93, s69, 0
	global_store_dword v239, v30, s[92:93]
	s_add_u32 s92, s68, 0x3b100
	s_addc_u32 s93, s69, 0
	global_store_dword v239, v31, s[92:93]
	s_waitcnt vmcnt(16)
	v_add_f32_e32 v0, v0, v240
	v_add_f32_e32 v1, v1, v241
	v_add_f32_e32 v2, v2, v242
	v_add_f32_e32 v3, v3, v243
	v_add_f32_e32 v4, v4, v244
	v_add_f32_e32 v5, v5, v245
	v_add_f32_e32 v6, v6, v246
	v_add_f32_e32 v7, v7, v247
	v_add_f32_e32 v8, v8, v248
	v_add_f32_e32 v9, v9, v249
	v_add_f32_e32 v10, v10, v250
	v_add_f32_e32 v11, v11, v251
	v_add_f32_e32 v12, v12, v252
	v_add_f32_e32 v13, v13, v253
	v_add_f32_e32 v14, v14, v254
	v_add_f32_e32 v15, v15, v255
	s_add_u32 s92, s68, 0x20180
	s_addc_u32 s93, s69, 0
	global_store_dword v239, v0, s[92:93]
	s_add_u32 s92, s68, 0x21180
	s_addc_u32 s93, s69, 0
	global_store_dword v239, v1, s[92:93]
	s_add_u32 s92, s68, 0x22180
	s_addc_u32 s93, s69, 0
	global_store_dword v239, v2, s[92:93]
	s_add_u32 s92, s68, 0x23180
	s_addc_u32 s93, s69, 0
	global_store_dword v239, v3, s[92:93]
	s_add_u32 s92, s68, 0x28180
	s_addc_u32 s93, s69, 0
	global_store_dword v239, v4, s[92:93]
	s_add_u32 s92, s68, 0x29180
	s_addc_u32 s93, s69, 0
	global_store_dword v239, v5, s[92:93]
	s_add_u32 s92, s68, 0x2a180
	s_addc_u32 s93, s69, 0
	global_store_dword v239, v6, s[92:93]
	s_add_u32 s92, s68, 0x2b180
	s_addc_u32 s93, s69, 0
	global_store_dword v239, v7, s[92:93]
	s_add_u32 s92, s68, 0x30180
	s_addc_u32 s93, s69, 0
	global_store_dword v239, v8, s[92:93]
	s_add_u32 s92, s68, 0x31180
	s_addc_u32 s93, s69, 0
	global_store_dword v239, v9, s[92:93]
	s_add_u32 s92, s68, 0x32180
	s_addc_u32 s93, s69, 0
	global_store_dword v239, v10, s[92:93]
	s_add_u32 s92, s68, 0x33180
	s_addc_u32 s93, s69, 0
	global_store_dword v239, v11, s[92:93]
	s_add_u32 s92, s68, 0x38180
	s_addc_u32 s93, s69, 0
	global_store_dword v239, v12, s[92:93]
	s_add_u32 s92, s68, 0x39180
	s_addc_u32 s93, s69, 0
	global_store_dword v239, v13, s[92:93]
	s_add_u32 s92, s68, 0x3a180
	s_addc_u32 s93, s69, 0
	global_store_dword v239, v14, s[92:93]
	s_add_u32 s92, s68, 0x3b180
	s_addc_u32 s93, s69, 0
	global_store_dword v239, v15, s[92:93]
	s_cmp_lg_u32 s91, 0
	s_cbranch_scc1 .LBB0_421

; DI f32x16 mfma32(bf16x8 a, bf16x8 b, f32x16 c) { return __builtin_amdgcn_mfma_f32_32x32x16_bf16(a, b, c, 0, 0, 0); }
; template <int NT, class Epi>
; DI void gemm_tile(const u16* __restrict__ A, int lda, const u16* __restrict__ Bt, int ldb, int K, int m0, int n0, const Epi& epi, char* smem) {
;     ...
;   for (int kt = 0; kt < nk; ++kt) {
; #pragma unroll
;     for (int i = 0; i < 4; ++i) *(u32x4*)(As + (lrow + 32 * i) * 72 + lch * 8) = ra[i];
; #pragma unroll
;     for (int i = 0; i < NB8; ++i) *(u32x4*)(Bs + (lrow + 32 * i) * 72 + lch * 8) = rb[i];
;     __syncthreads();
;     if (kt + 1 < nk) {
;       const int k0 = (kt + 1) * 64;
; #pragma unroll
;       for (int i = 0; i < 4; ++i) ra[i] = *(const u32x4*)(Ap + (size_t)(32 * i) * lda + k0);
; #pragma unroll
;       for (int i = 0; i < NB8; ++i) rb[i] = *(const u32x4*)(Bp + (size_t)(32 * i) * ldb + k0);
;     }
; #pragma unroll
;     for (int ks = 0; ks < 4; ++ks) {
;       bf16x8 a[2], b[NT];
; #pragma unroll
;       for (int mt = 0; mt < 2; ++mt) a[mt] = *(const bf16x8*)(As + (wm * 64 + mt * 32 + r) * 72 + ks * 16 + h * 8);
; #pragma unroll
;       for (int nt = 0; nt < NT; ++nt) b[nt] = *(const bf16x8*)(Bs + (wn * 32 * NT + nt * 32 + r) * 72 + ks * 16 + h * 8);
; #pragma unroll
;       for (int mt = 0; mt < 2; ++mt)
; #pragma unroll
;         for (int nt = 0; nt < NT; ++nt) acc[mt][nt] = mfma32(a[mt], b[nt], acc[mt][nt]);
;     }
;     __syncthreads();
;   }
.LBB0_643:
	s_waitcnt vmcnt(11)
	ds_write_b128 v197, v[128:131]
	s_waitcnt vmcnt(10)
	ds_write_b128 v197, v[132:135] offset:4608
	s_waitcnt vmcnt(9)
	ds_write_b128 v197, v[136:139] offset:9216
	s_waitcnt vmcnt(8)
	ds_write_b128 v197, v[140:143] offset:13824
	s_waitcnt vmcnt(7)
	ds_write_b128 v197, v[144:147] offset:18432
	s_waitcnt vmcnt(6)
	ds_write_b128 v197, v[148:151] offset:23040
	s_waitcnt vmcnt(5)
	ds_write_b128 v197, v[152:155] offset:27648
	s_waitcnt vmcnt(4)
	ds_write_b128 v197, v[156:159] offset:32256
	s_waitcnt vmcnt(3)
	ds_write_b128 v197, v[160:163] offset:36864
	s_waitcnt vmcnt(2)
	ds_write_b128 v197, v[164:167] offset:41472
	s_waitcnt vmcnt(1)
	ds_write_b128 v197, v[168:171] offset:46080
	s_waitcnt vmcnt(0)
	ds_write_b128 v197, v[172:175] offset:50688
	s_waitcnt lgkmcnt(0)
	s_barrier
	ds_read_b128 v[128:131], v199
	ds_read_b128 v[132:135], v206 offset:18432
	ds_read_b128 v[136:139], v199 offset:32
	ds_read_b128 v[140:143], v206 offset:18464
	ds_read_b128 v[144:147], v206 offset:23040
	ds_read_b128 v[148:151], v206 offset:23072
	ds_read_b128 v[152:155], v206 offset:27648
	ds_read_b128 v[156:159], v206 offset:27680
	ds_read_b128 v[160:163], v206 offset:32256
	ds_read_b128 v[164:167], v206 offset:32288
	s_waitcnt lgkmcnt(8)
	v_mfma_f32_32x32x16_bf16 v[112:127], v[128:131], v[132:135], v[112:127]
	s_waitcnt lgkmcnt(5)
	v_mfma_f32_32x32x16_bf16 v[96:111], v[128:131], v[144:147], v[96:111]
	s_waitcnt lgkmcnt(3)
	v_mfma_f32_32x32x16_bf16 v[80:95], v[128:131], v[152:155], v[80:95]
	s_waitcnt lgkmcnt(1)
	v_mfma_f32_32x32x16_bf16 v[64:79], v[128:131], v[160:163], v[64:79]
	ds_read_b128 v[128:131], v199 offset:4608
	ds_read_b128 v[168:171], v199 offset:4640
	s_waitcnt lgkmcnt(1)
	v_mfma_f32_32x32x16_bf16 v[48:63], v[128:131], v[132:135], v[48:63]
	v_mfma_f32_32x32x16_bf16 v[32:47], v[128:131], v[144:147], v[32:47]
	v_mfma_f32_32x32x16_bf16 v[16:31], v[128:131], v[152:155], v[16:31]
	v_mfma_f32_32x32x16_bf16 v[112:127], v[136:139], v[140:143], v[112:127]
	v_mfma_f32_32x32x16_bf16 v[96:111], v[136:139], v[148:151], v[96:111]
	v_mfma_f32_32x32x16_bf16 v[80:95], v[136:139], v[156:159], v[80:95]
	v_mfma_f32_32x32x16_bf16 v[64:79], v[136:139], v[164:167], v[64:79]
	v_mfma_f32_32x32x16_bf16 v[0:15], v[128:131], v[160:163], v[0:15]
	s_waitcnt lgkmcnt(0)
	v_mfma_f32_32x32x16_bf16 v[48:63], v[168:171], v[140:143], v[48:63]
	ds_read_b128 v[128:131], v199 offset:64
	ds_read_b128 v[132:135], v206 offset:18496
	ds_read_b128 v[136:139], v199 offset:96
	ds_read_b128 v[140:143], v206 offset:18528
	v_mfma_f32_32x32x16_bf16 v[32:47], v[168:171], v[148:151], v[32:47]
	ds_read_b128 v[144:147], v206 offset:23104
	ds_read_b128 v[148:151], v206 offset:23136
	ds_read_b128 v[152:155], v206 offset:27712
	ds_read_b128 v[172:175], v206 offset:27744
	v_mfma_f32_32x32x16_bf16 v[16:31], v[168:171], v[156:159], v[16:31]
	ds_read_b128 v[156:159], v206 offset:32320
	ds_read_b128 v[208:211], v206 offset:32352
	s_waitcnt lgkmcnt(8)
	v_mfma_f32_32x32x16_bf16 v[112:127], v[128:131], v[132:135], v[112:127]
	s_waitcnt lgkmcnt(5)
	v_mfma_f32_32x32x16_bf16 v[96:111], v[128:131], v[144:147], v[96:111]
	s_waitcnt lgkmcnt(3)
	v_mfma_f32_32x32x16_bf16 v[80:95], v[128:131], v[152:155], v[80:95]
	s_waitcnt lgkmcnt(1)
	v_mfma_f32_32x32x16_bf16 v[64:79], v[128:131], v[156:159], v[64:79]
	ds_read_b128 v[128:131], v199 offset:4672
	ds_read_b128 v[230:233], v199 offset:4704
	s_waitcnt lgkmcnt(1)
	v_mfma_f32_32x32x16_bf16 v[48:63], v[128:131], v[132:135], v[48:63]
	v_lshl_add_u64 v[132:133], v[202:203], 0, s[20:21]
	v_lshl_add_u64 v[134:135], v[204:205], 0, s[20:21]
	s_add_u32 s20, s20, 0x80
	s_addc_u32 s21, s21, 0
	s_cmpk_lg_i32 s20, 0x780
	v_mfma_f32_32x32x16_bf16 v[0:15], v[168:171], v[164:167], v[0:15]
	v_mfma_f32_32x32x16_bf16 v[32:47], v[128:131], v[144:147], v[32:47]
	v_add_co_u32_e32 v144, vcc, s28, v132
	s_nop 1
	v_addc_co_u32_e32 v145, vcc, 0, v133, vcc
	v_add_co_u32_e32 v146, vcc, s29, v132
	v_mfma_f32_32x32x16_bf16 v[16:31], v[128:131], v[152:155], v[16:31]
	s_nop 0
	v_addc_co_u32_e32 v147, vcc, 0, v133, vcc
	v_add_co_u32_e32 v152, vcc, s30, v132
	s_nop 1
	v_addc_co_u32_e32 v153, vcc, 0, v133, vcc
	v_add_co_u32_e32 v154, vcc, s31, v132
	v_mfma_f32_32x32x16_bf16 v[0:15], v[128:131], v[156:159], v[0:15]
	s_nop 0
	v_addc_co_u32_e32 v155, vcc, 0, v133, vcc
	v_add_co_u32_e32 v156, vcc, s34, v134
	s_nop 1
	v_addc_co_u32_e32 v157, vcc, 0, v135, vcc
	v_add_co_u32_e32 v158, vcc, s35, v134
	v_mfma_f32_32x32x16_bf16 v[112:127], v[136:139], v[140:143], v[112:127]
	s_nop 0
	v_addc_co_u32_e32 v159, vcc, 0, v135, vcc
	v_add_co_u32_e32 v160, vcc, s36, v134
	s_nop 1
	v_addc_co_u32_e32 v161, vcc, 0, v135, vcc
	v_add_co_u32_e32 v162, vcc, s37, v134
	v_mfma_f32_32x32x16_bf16 v[96:111], v[136:139], v[148:151], v[96:111]
	s_nop 0
	v_addc_co_u32_e32 v163, vcc, 0, v135, vcc
	v_add_co_u32_e32 v164, vcc, s38, v134
	s_nop 1
	v_addc_co_u32_e32 v165, vcc, 0, v135, vcc
	v_add_co_u32_e32 v166, vcc, s39, v134
	v_mfma_f32_32x32x16_bf16 v[80:95], v[136:139], v[172:175], v[80:95]
	s_nop 0
	v_addc_co_u32_e32 v167, vcc, 0, v135, vcc
	v_add_co_u32_e32 v168, vcc, s40, v134
	s_nop 1
	v_addc_co_u32_e32 v169, vcc, 0, v135, vcc
	v_add_co_u32_e32 v234, vcc, s41, v134
	v_mfma_f32_32x32x16_bf16 v[64:79], v[136:139], v[208:211], v[64:79]
	s_nop 0
	v_addc_co_u32_e32 v235, vcc, 0, v135, vcc
	s_waitcnt lgkmcnt(0)
	v_mfma_f32_32x32x16_bf16 v[48:63], v[230:233], v[140:143], v[48:63]
	global_load_dwordx4 v[128:131], v[144:145], off offset:128
	global_load_dwordx4 v[132:135], v[146:147], off offset:128
	global_load_dwordx4 v[136:139], v[152:153], off offset:128
	global_load_dwordx4 v[140:143], v[154:155], off offset:128
	v_mfma_f32_32x32x16_bf16 v[32:47], v[230:233], v[148:151], v[32:47]
	global_load_dwordx4 v[144:147], v[156:157], off offset:128
	global_load_dwordx4 v[148:151], v[158:159], off offset:128
	global_load_dwordx4 v[152:155], v[160:161], off offset:128
	s_nop 0
	global_load_dwordx4 v[156:159], v[162:163], off offset:128
	s_nop 0
	global_load_dwordx4 v[160:163], v[164:165], off offset:128
	s_nop 0
	global_load_dwordx4 v[164:167], v[166:167], off offset:128
	s_nop 0
	global_load_dwordx4 v[168:171], v[168:169], off offset:128
	v_mfma_f32_32x32x16_bf16 v[16:31], v[230:233], v[172:175], v[16:31]
	global_load_dwordx4 v[172:175], v[234:235], off offset:128
	s_barrier
; DI int crow(int i, int h) { return (i & 3) + 8 * (i >> 2) + 4 * h; }
; DI f32x16 mfma32(bf16x8 a, bf16x8 b, f32x16 c) { return __builtin_amdgcn_mfma_f32_32x32x16_bf16(a, b, c, 0, 0, 0); }
; template <int NT, class Epi>
; DI void gemm_tile(const u16* __restrict__ A, int lda, const u16* __restrict__ Bt, int ldb, int K, int m0, int n0, const Epi& epi, char* smem) {
;     ...
;   for (int kt = 0; kt < nk; ++kt) {
; #pragma unroll
;     for (int i = 0; i < 4; ++i) *(u32x4*)(As + (lrow + 32 * i) * 72 + lch * 8) = ra[i];
; #pragma unroll
;     for (int i = 0; i < NB8; ++i) *(u32x4*)(Bs + (lrow + 32 * i) * 72 + lch * 8) = rb[i];
;     __syncthreads();
;     if (kt + 1 < nk) {
;       const int k0 = (kt + 1) * 64;
; #pragma unroll
;       for (int i = 0; i < 4; ++i) ra[i] = *(const u32x4*)(Ap + (size_t)(32 * i) * lda + k0);
; #pragma unroll
;       for (int i = 0; i < NB8; ++i) rb[i] = *(const u32x4*)(Bp + (size_t)(32 * i) * ldb + k0);
;     }
; #pragma unroll
;     for (int ks = 0; ks < 4; ++ks) {
;       bf16x8 a[2], b[NT];
; #pragma unroll
;       for (int mt = 0; mt < 2; ++mt) a[mt] = *(const bf16x8*)(As + (wm * 64 + mt * 32 + r) * 72 + ks * 16 + h * 8);
; #pragma unroll
;       for (int nt = 0; nt < NT; ++nt) b[nt] = *(const bf16x8*)(Bs + (wn * 32 * NT + nt * 32 + r) * 72 + ks * 16 + h * 8);
; #pragma unroll
;       for (int mt = 0; mt < 2; ++mt)
; #pragma unroll
;         for (int nt = 0; nt < NT; ++nt) acc[mt][nt] = mfma32(a[mt], b[nt], acc[mt][nt]);
;     }
;     __syncthreads();
;   }
; #pragma unroll
;   for (int mt = 0; mt < 2; ++mt)
; #pragma unroll
;     for (int nt = 0; nt < NT; ++nt) epi(acc[mt][nt], m0 + wm * 64 + mt * 32, n0 + wn * 32 * NT + nt * 32, lane);
;   DI void operator()(const f32x16& acc, int row0, int col0, int lane) const {
;     const int r = lane & 31, h = lane >> 5, col = col0 + r;
; #pragma unroll
;     for (int i = 0; i < 16; ++i) { float* q = H + (size_t)(row0 + crow(i, h)) * DM + col; *q = *q + acc[i]; }
;   }
	v_mfma_f32_32x32x16_bf16 v[0:15], v[230:233], v[208:211], v[0:15]
	s_cbranch_scc1 .LBB0_643
	s_waitcnt vmcnt(11)
	ds_write_b128 v197, v[128:131]
	s_waitcnt vmcnt(10)
	ds_write_b128 v197, v[132:135] offset:4608
	s_waitcnt vmcnt(9)
	ds_write_b128 v197, v[136:139] offset:9216
	s_waitcnt vmcnt(8)
	ds_write_b128 v197, v[140:143] offset:13824
	s_waitcnt vmcnt(7)
	ds_write_b128 v197, v[144:147] offset:18432
	s_waitcnt vmcnt(6)
	ds_write_b128 v197, v[148:151] offset:23040
	s_waitcnt vmcnt(5)
	ds_write_b128 v197, v[152:155] offset:27648
	s_waitcnt vmcnt(4)
	ds_write_b128 v197, v[156:159] offset:32256
	s_waitcnt vmcnt(3)
	ds_write_b128 v197, v[160:163] offset:36864
	s_waitcnt vmcnt(2)
	ds_write_b128 v197, v[164:167] offset:41472
	s_waitcnt vmcnt(1)
	ds_write_b128 v197, v[168:171] offset:46080
	s_waitcnt vmcnt(0)
	ds_write_b128 v197, v[172:175] offset:50688
	s_waitcnt lgkmcnt(0)
	s_barrier
	ds_read_b128 v[128:131], v199 offset:4608
	ds_read_b128 v[132:135], v206 offset:23040
	ds_read_b128 v[136:139], v206 offset:27648
	ds_read_b128 v[140:143], v206 offset:32256
	ds_read_b128 v[144:147], v199
	ds_read_b128 v[148:151], v199 offset:32
	ds_read_b128 v[152:155], v206 offset:18432
	ds_read_b128 v[156:159], v206 offset:18464
	s_waitcnt lgkmcnt(1)
	v_mfma_f32_32x32x16_bf16 v[112:127], v[144:147], v[152:155], v[112:127]
	v_add_lshl_u32 v188, v181, s43, 12
	s_add_i32 s42, s42, s78
	s_add_i32 s22, s22, s23
	s_cmpk_lt_u32 s42, 0x100
	v_mfma_f32_32x32x16_bf16 v[96:111], v[144:147], v[132:135], v[96:111]
	v_mfma_f32_32x32x16_bf16 v[80:95], v[144:147], v[136:139], v[80:95]
	v_mfma_f32_32x32x16_bf16 v[64:79], v[144:147], v[140:143], v[64:79]
	v_mfma_f32_32x32x16_bf16 v[48:63], v[128:131], v[152:155], v[48:63]
	v_or_b32_e32 v154, 0x3000, v188
	v_mov_b32_e32 v155, v189
	v_or_b32_e32 v152, 0x8000, v188
	v_mov_b32_e32 v153, v189
	v_mfma_f32_32x32x16_bf16 v[32:47], v[128:131], v[132:135], v[32:47]
	v_mfma_f32_32x32x16_bf16 v[16:31], v[128:131], v[136:139], v[16:31]
	v_mfma_f32_32x32x16_bf16 v[0:15], v[128:131], v[140:143], v[0:15]
	ds_read_b128 v[128:131], v199 offset:4640
	ds_read_b128 v[132:135], v206 offset:23072
	ds_read_b128 v[136:139], v206 offset:27680
	ds_read_b128 v[140:143], v206 offset:32288
	s_waitcnt lgkmcnt(4)
	v_mfma_f32_32x32x16_bf16 v[112:127], v[148:151], v[156:159], v[112:127]
	s_waitcnt lgkmcnt(2)
	v_mfma_f32_32x32x16_bf16 v[96:111], v[148:151], v[132:135], v[96:111]
	s_waitcnt lgkmcnt(1)
	v_mfma_f32_32x32x16_bf16 v[80:95], v[148:151], v[136:139], v[80:95]
	s_waitcnt lgkmcnt(0)
	v_mfma_f32_32x32x16_bf16 v[64:79], v[148:151], v[140:143], v[64:79]
	v_mfma_f32_32x32x16_bf16 v[48:63], v[128:131], v[156:159], v[48:63]
	v_or_b32_e32 v158, 0x1000, v188
	v_mov_b32_e32 v159, v189
	v_or_b32_e32 v156, 0x2000, v188
	v_mov_b32_e32 v157, v189
	v_mfma_f32_32x32x16_bf16 v[32:47], v[128:131], v[132:135], v[32:47]
	v_mfma_f32_32x32x16_bf16 v[16:31], v[128:131], v[136:139], v[16:31]
	v_mfma_f32_32x32x16_bf16 v[0:15], v[128:131], v[140:143], v[0:15]
	ds_read_b128 v[128:131], v199 offset:64
	ds_read_b128 v[132:135], v199 offset:4672
	ds_read_b128 v[136:139], v206 offset:18496
	ds_read_b128 v[140:143], v206 offset:23104
	ds_read_b128 v[144:147], v206 offset:27712
	ds_read_b128 v[148:151], v206 offset:32320
	s_waitcnt lgkmcnt(3)
	v_mfma_f32_32x32x16_bf16 v[112:127], v[128:131], v[136:139], v[112:127]
	s_waitcnt lgkmcnt(2)
	v_mfma_f32_32x32x16_bf16 v[96:111], v[128:131], v[140:143], v[96:111]
	s_waitcnt lgkmcnt(1)
	v_mfma_f32_32x32x16_bf16 v[80:95], v[128:131], v[144:147], v[80:95]
	s_waitcnt lgkmcnt(0)
	v_mfma_f32_32x32x16_bf16 v[64:79], v[128:131], v[148:151], v[64:79]
	v_mfma_f32_32x32x16_bf16 v[48:63], v[132:135], v[136:139], v[48:63]
	v_mfma_f32_32x32x16_bf16 v[32:47], v[132:135], v[140:143], v[32:47]
	v_mfma_f32_32x32x16_bf16 v[16:31], v[132:135], v[144:147], v[16:31]
	v_mfma_f32_32x32x16_bf16 v[0:15], v[132:135], v[148:151], v[0:15]
	ds_read_b128 v[128:131], v199 offset:96
	ds_read_b128 v[132:135], v199 offset:4704
	ds_read_b128 v[136:139], v206 offset:18528
	ds_read_b128 v[140:143], v206 offset:23136
	ds_read_b128 v[144:147], v206 offset:27744
	ds_read_b128 v[148:151], v206 offset:32352
	s_waitcnt lgkmcnt(0)
	s_barrier
	v_mfma_f32_32x32x16_bf16 v[112:127], v[128:131], v[136:139], v[112:127]
	v_mfma_f32_32x32x16_bf16 v[96:111], v[128:131], v[140:143], v[96:111]
	v_mfma_f32_32x32x16_bf16 v[80:95], v[128:131], v[144:147], v[80:95]
	v_mfma_f32_32x32x16_bf16 v[64:79], v[128:131], v[148:151], v[64:79]
	v_mfma_f32_32x32x16_bf16 v[0:15], v[132:135], v[148:151], v[0:15]
	v_mfma_f32_32x32x16_bf16 v[16:31], v[132:135], v[144:147], v[16:31]
	v_mfma_f32_32x32x16_bf16 v[32:47], v[132:135], v[140:143], v[32:47]
	v_mfma_f32_32x32x16_bf16 v[48:63], v[132:135], v[136:139], v[48:63]
	s_cselect_b32 s91, 1, 0
	v_or_b32_e32 v239, s44, v179
	v_lshlrev_b32_e32 v239, 2, v239
	v_add_u32_e32 v239, v239, v188
	s_add_u32 s92, s68, 0x0
	s_addc_u32 s93, s69, 0
	global_load_dword v128, v239, s[92:93]
	s_add_u32 s92, s68, 0x1000
	s_addc_u32 s93, s69, 0
	global_load_dword v129, v239, s[92:93]
	s_add_u32 s92, s68, 0x2000
	s_addc_u32 s93, s69, 0
	global_load_dword v130, v239, s[92:93]
	s_add_u32 s92, s68, 0x3000
	s_addc_u32 s93, s69, 0
	global_load_dword v131, v239, s[92:93]
	s_add_u32 s92, s68, 0x8000
	s_addc_u32 s93, s69, 0
	global_load_dword v132, v239, s[92:93]
	s_add_u32 s92, s68, 0x9000
	s_addc_u32 s93, s69, 0
	global_load_dword v133, v239, s[92:93]
	s_add_u32 s92, s68, 0xa000
	s_addc_u32 s93, s69, 0
	global_load_dword v134, v239, s[92:93]
	s_add_u32 s92, s68, 0xb000
	s_addc_u32 s93, s69, 0
	global_load_dword v135, v239, s[92:93]
	s_add_u32 s92, s68, 0x10000
	s_addc_u32 s93, s69, 0
; DI int crow(int i, int h) { return (i & 3) + 8 * (i >> 2) + 4 * h; }
; template <int NT, class Epi>
; DI void gemm_tile(const u16* __restrict__ A, int lda, const u16* __restrict__ Bt, int ldb, int K, int m0, int n0, const Epi& epi, char* smem) {
;     ...
; #pragma unroll
;   for (int mt = 0; mt < 2; ++mt)
; #pragma unroll
;     for (int nt = 0; nt < NT; ++nt) epi(acc[mt][nt], m0 + wm * 64 + mt * 32, n0 + wn * 32 * NT + nt * 32, lane);
;   DI void operator()(const f32x16& acc, int row0, int col0, int lane) const {
;     const int r = lane & 31, h = lane >> 5, col = col0 + r;
; #pragma unroll
;     for (int i = 0; i < 16; ++i) { float* q = H + (size_t)(row0 + crow(i, h)) * DM + col; *q = *q + acc[i]; }
;   }
	global_load_dword v136, v239, s[92:93]
	s_add_u32 s92, s68, 0x11000
	s_addc_u32 s93, s69, 0
	global_load_dword v137, v239, s[92:93]
	s_add_u32 s92, s68, 0x12000
	s_addc_u32 s93, s69, 0
	global_load_dword v138, v239, s[92:93]
	s_add_u32 s92, s68, 0x13000
	s_addc_u32 s93, s69, 0
	global_load_dword v139, v239, s[92:93]
	s_add_u32 s92, s68, 0x18000
	s_addc_u32 s93, s69, 0
	global_load_dword v140, v239, s[92:93]
	s_add_u32 s92, s68, 0x19000
	s_addc_u32 s93, s69, 0
	global_load_dword v141, v239, s[92:93]
	s_add_u32 s92, s68, 0x1a000
	s_addc_u32 s93, s69, 0
	global_load_dword v142, v239, s[92:93]
	s_add_u32 s92, s68, 0x1b000
	s_addc_u32 s93, s69, 0
	global_load_dword v143, v239, s[92:93]
	s_add_u32 s92, s68, 0x80
	s_addc_u32 s93, s69, 0
	global_load_dword v240, v239, s[92:93]
	s_add_u32 s92, s68, 0x1080
	s_addc_u32 s93, s69, 0
	global_load_dword v241, v239, s[92:93]
	s_add_u32 s92, s68, 0x2080
	s_addc_u32 s93, s69, 0
	global_load_dword v242, v239, s[92:93]
	s_add_u32 s92, s68, 0x3080
	s_addc_u32 s93, s69, 0
	global_load_dword v243, v239, s[92:93]
	s_add_u32 s92, s68, 0x8080
	s_addc_u32 s93, s69, 0
	global_load_dword v244, v239, s[92:93]
	s_add_u32 s92, s68, 0x9080
	s_addc_u32 s93, s69, 0
	global_load_dword v245, v239, s[92:93]
	s_add_u32 s92, s68, 0xa080
	s_addc_u32 s93, s69, 0
	global_load_dword v246, v239, s[92:93]
	s_add_u32 s92, s68, 0xb080
	s_addc_u32 s93, s69, 0
	global_load_dword v247, v239, s[92:93]
	s_add_u32 s92, s68, 0x10080
	s_addc_u32 s93, s69, 0
	global_load_dword v248, v239, s[92:93]
	s_add_u32 s92, s68, 0x11080
	s_addc_u32 s93, s69, 0
	global_load_dword v249, v239, s[92:93]
	s_add_u32 s92, s68, 0x12080
	s_addc_u32 s93, s69, 0
	global_load_dword v250, v239, s[92:93]
	s_add_u32 s92, s68, 0x13080
	s_addc_u32 s93, s69, 0
	global_load_dword v251, v239, s[92:93]
	s_add_u32 s92, s68, 0x18080
	s_addc_u32 s93, s69, 0
	global_load_dword v252, v239, s[92:93]
	s_add_u32 s92, s68, 0x19080
	s_addc_u32 s93, s69, 0
	global_load_dword v253, v239, s[92:93]
	s_add_u32 s92, s68, 0x1a080
	s_addc_u32 s93, s69, 0
	global_load_dword v254, v239, s[92:93]
	s_add_u32 s92, s68, 0x1b080
	s_addc_u32 s93, s69, 0
	global_load_dword v255, v239, s[92:93]
	s_waitcnt vmcnt(16)
	v_add_f32_e32 v112, v112, v128
	v_add_f32_e32 v113, v113, v129
	v_add_f32_e32 v114, v114, v130
	v_add_f32_e32 v115, v115, v131
	v_add_f32_e32 v116, v116, v132
	v_add_f32_e32 v117, v117, v133
	v_add_f32_e32 v118, v118, v134
	v_add_f32_e32 v119, v119, v135
	v_add_f32_e32 v120, v120, v136
	v_add_f32_e32 v121, v121, v137
	v_add_f32_e32 v122, v122, v138
	v_add_f32_e32 v123, v123, v139
	v_add_f32_e32 v124, v124, v140
	v_add_f32_e32 v125, v125, v141
	v_add_f32_e32 v126, v126, v142
	v_add_f32_e32 v127, v127, v143
	s_add_u32 s92, s68, 0x0
	s_addc_u32 s93, s69, 0
	global_store_dword v239, v112, s[92:93]
	s_add_u32 s92, s68, 0x1000
	s_addc_u32 s93, s69, 0
	global_store_dword v239, v113, s[92:93]
	s_add_u32 s92, s68, 0x2000
	s_addc_u32 s93, s69, 0
	global_store_dword v239, v114, s[92:93]
	s_add_u32 s92, s68, 0x3000
	s_addc_u32 s93, s69, 0
	global_store_dword v239, v115, s[92:93]
	s_add_u32 s92, s68, 0x8000
	s_addc_u32 s93, s69, 0
	global_store_dword v239, v116, s[92:93]
	s_add_u32 s92, s68, 0x9000
	s_addc_u32 s93, s69, 0
	global_store_dword v239, v117, s[92:93]
	s_add_u32 s92, s68, 0xa000
	s_addc_u32 s93, s69, 0
	global_store_dword v239, v118, s[92:93]
	s_add_u32 s92, s68, 0xb000
	s_addc_u32 s93, s69, 0
	global_store_dword v239, v119, s[92:93]
	s_add_u32 s92, s68, 0x10000
	s_addc_u32 s93, s69, 0
	global_store_dword v239, v120, s[92:93]
	s_add_u32 s92, s68, 0x11000
	s_addc_u32 s93, s69, 0
	global_store_dword v239, v121, s[92:93]
	s_add_u32 s92, s68, 0x12000
	s_addc_u32 s93, s69, 0
	global_store_dword v239, v122, s[92:93]
	s_add_u32 s92, s68, 0x13000
	s_addc_u32 s93, s69, 0
	global_store_dword v239, v123, s[92:93]
	s_add_u32 s92, s68, 0x18000
	s_addc_u32 s93, s69, 0
	global_store_dword v239, v124, s[92:93]
	s_add_u32 s92, s68, 0x19000
	s_addc_u32 s93, s69, 0
	global_store_dword v239, v125, s[92:93]
	s_add_u32 s92, s68, 0x1a000
	s_addc_u32 s93, s69, 0
	global_store_dword v239, v126, s[92:93]
	s_add_u32 s92, s68, 0x1b000
	s_addc_u32 s93, s69, 0
	global_store_dword v239, v127, s[92:93]
	s_add_u32 s92, s68, 0x100
	s_addc_u32 s93, s69, 0
	global_load_dword v128, v239, s[92:93]
	s_add_u32 s92, s68, 0x1100
	s_addc_u32 s93, s69, 0
	global_load_dword v129, v239, s[92:93]
	s_add_u32 s92, s68, 0x2100
	s_addc_u32 s93, s69, 0
	global_load_dword v130, v239, s[92:93]
	s_add_u32 s92, s68, 0x3100
	s_addc_u32 s93, s69, 0
	global_load_dword v131, v239, s[92:93]
	s_add_u32 s92, s68, 0x8100
	s_addc_u32 s93, s69, 0
	global_load_dword v132, v239, s[92:93]
	s_add_u32 s92, s68, 0x9100
	s_addc_u32 s93, s69, 0
	global_load_dword v133, v239, s[92:93]
	s_add_u32 s92, s68, 0xa100
	s_addc_u32 s93, s69, 0
	global_load_dword v134, v239, s[92:93]
	s_add_u32 s92, s68, 0xb100
	s_addc_u32 s93, s69, 0
	global_load_dword v135, v239, s[92:93]
	s_add_u32 s92, s68, 0x10100
	s_addc_u32 s93, s69, 0
	global_load_dword v136, v239, s[92:93]
	s_add_u32 s92, s68, 0x11100
	s_addc_u32 s93, s69, 0
	global_load_dword v137, v239, s[92:93]
	s_add_u32 s92, s68, 0x12100
	s_addc_u32 s93, s69, 0
	global_load_dword v138, v239, s[92:93]
	s_add_u32 s92, s68, 0x13100
	s_addc_u32 s93, s69, 0
	global_load_dword v139, v239, s[92:93]
	s_add_u32 s92, s68, 0x18100
	s_addc_u32 s93, s69, 0
	global_load_dword v140, v239, s[92:93]
	s_add_u32 s92, s68, 0x19100
	s_addc_u32 s93, s69, 0
	global_load_dword v141, v239, s[92:93]
	s_add_u32 s92, s68, 0x1a100
	s_addc_u32 s93, s69, 0
	global_load_dword v142, v239, s[92:93]
	s_add_u32 s92, s68, 0x1b100
	s_addc_u32 s93, s69, 0
	global_load_dword v143, v239, s[92:93]
	s_waitcnt vmcnt(32)
; DI int crow(int i, int h) { return (i & 3) + 8 * (i >> 2) + 4 * h; }
; template <int NT, class Epi>
; DI void gemm_tile(const u16* __restrict__ A, int lda, const u16* __restrict__ Bt, int ldb, int K, int m0, int n0, const Epi& epi, char* smem) {
;     ...
; #pragma unroll
;   for (int mt = 0; mt < 2; ++mt)
; #pragma unroll
;     for (int nt = 0; nt < NT; ++nt) epi(acc[mt][nt], m0 + wm * 64 + mt * 32, n0 + wn * 32 * NT + nt * 32, lane);
;   DI void operator()(const f32x16& acc, int row0, int col0, int lane) const {
;     const int r = lane & 31, h = lane >> 5, col = col0 + r;
; #pragma unroll
;     for (int i = 0; i < 16; ++i) { float* q = H + (size_t)(row0 + crow(i, h)) * DM + col; *q = *q + acc[i]; }
;   }
	v_add_f32_e32 v96, v96, v240
	v_add_f32_e32 v97, v97, v241
	v_add_f32_e32 v98, v98, v242
	v_add_f32_e32 v99, v99, v243
	v_add_f32_e32 v100, v100, v244
	v_add_f32_e32 v101, v101, v245
	v_add_f32_e32 v102, v102, v246
	v_add_f32_e32 v103, v103, v247
	v_add_f32_e32 v104, v104, v248
	v_add_f32_e32 v105, v105, v249
	v_add_f32_e32 v106, v106, v250
	v_add_f32_e32 v107, v107, v251
	v_add_f32_e32 v108, v108, v252
	v_add_f32_e32 v109, v109, v253
	v_add_f32_e32 v110, v110, v254
	v_add_f32_e32 v111, v111, v255
	s_add_u32 s92, s68, 0x80
	s_addc_u32 s93, s69, 0
	global_store_dword v239, v96, s[92:93]
	s_add_u32 s92, s68, 0x1080
	s_addc_u32 s93, s69, 0
	global_store_dword v239, v97, s[92:93]
	s_add_u32 s92, s68, 0x2080
	s_addc_u32 s93, s69, 0
	global_store_dword v239, v98, s[92:93]
	s_add_u32 s92, s68, 0x3080
	s_addc_u32 s93, s69, 0
	global_store_dword v239, v99, s[92:93]
	s_add_u32 s92, s68, 0x8080
	s_addc_u32 s93, s69, 0
	global_store_dword v239, v100, s[92:93]
	s_add_u32 s92, s68, 0x9080
	s_addc_u32 s93, s69, 0
	global_store_dword v239, v101, s[92:93]
	s_add_u32 s92, s68, 0xa080
	s_addc_u32 s93, s69, 0
	global_store_dword v239, v102, s[92:93]
	s_add_u32 s92, s68, 0xb080
	s_addc_u32 s93, s69, 0
	global_store_dword v239, v103, s[92:93]
	s_add_u32 s92, s68, 0x10080
	s_addc_u32 s93, s69, 0
	global_store_dword v239, v104, s[92:93]
	s_add_u32 s92, s68, 0x11080
	s_addc_u32 s93, s69, 0
	global_store_dword v239, v105, s[92:93]
	s_add_u32 s92, s68, 0x12080
	s_addc_u32 s93, s69, 0
	global_store_dword v239, v106, s[92:93]
	s_add_u32 s92, s68, 0x13080
	s_addc_u32 s93, s69, 0
	global_store_dword v239, v107, s[92:93]
	s_add_u32 s92, s68, 0x18080
	s_addc_u32 s93, s69, 0
	global_store_dword v239, v108, s[92:93]
	s_add_u32 s92, s68, 0x19080
	s_addc_u32 s93, s69, 0
	global_store_dword v239, v109, s[92:93]
	s_add_u32 s92, s68, 0x1a080
	s_addc_u32 s93, s69, 0
	global_store_dword v239, v110, s[92:93]
	s_add_u32 s92, s68, 0x1b080
	s_addc_u32 s93, s69, 0
	global_store_dword v239, v111, s[92:93]
	s_add_u32 s92, s68, 0x180
	s_addc_u32 s93, s69, 0
	global_load_dword v240, v239, s[92:93]
	s_add_u32 s92, s68, 0x1180
	s_addc_u32 s93, s69, 0
	global_load_dword v241, v239, s[92:93]
	s_add_u32 s92, s68, 0x2180
	s_addc_u32 s93, s69, 0
	global_load_dword v242, v239, s[92:93]
	s_add_u32 s92, s68, 0x3180
	s_addc_u32 s93, s69, 0
	global_load_dword v243, v239, s[92:93]
	s_add_u32 s92, s68, 0x8180
	s_addc_u32 s93, s69, 0
	global_load_dword v244, v239, s[92:93]
	s_add_u32 s92, s68, 0x9180
	s_addc_u32 s93, s69, 0
	global_load_dword v245, v239, s[92:93]
	s_add_u32 s92, s68, 0xa180
	s_addc_u32 s93, s69, 0
	global_load_dword v246, v239, s[92:93]
	s_add_u32 s92, s68, 0xb180
	s_addc_u32 s93, s69, 0
	global_load_dword v247, v239, s[92:93]
	s_add_u32 s92, s68, 0x10180
	s_addc_u32 s93, s69, 0
	global_load_dword v248, v239, s[92:93]
	s_add_u32 s92, s68, 0x11180
	s_addc_u32 s93, s69, 0
	global_load_dword v249, v239, s[92:93]
	s_add_u32 s92, s68, 0x12180
	s_addc_u32 s93, s69, 0
	global_load_dword v250, v239, s[92:93]
	s_add_u32 s92, s68, 0x13180
	s_addc_u32 s93, s69, 0
	global_load_dword v251, v239, s[92:93]
	s_add_u32 s92, s68, 0x18180
	s_addc_u32 s93, s69, 0
	global_load_dword v252, v239, s[92:93]
	s_add_u32 s92, s68, 0x19180
	s_addc_u32 s93, s69, 0
	global_load_dword v253, v239, s[92:93]
	s_add_u32 s92, s68, 0x1a180
	s_addc_u32 s93, s69, 0
	global_load_dword v254, v239, s[92:93]
	s_add_u32 s92, s68, 0x1b180
	s_addc_u32 s93, s69, 0
	global_load_dword v255, v239, s[92:93]
	s_waitcnt vmcnt(32)
	v_add_f32_e32 v80, v80, v128
	v_add_f32_e32 v81, v81, v129
	v_add_f32_e32 v82, v82, v130
	v_add_f32_e32 v83, v83, v131
	v_add_f32_e32 v84, v84, v132
	v_add_f32_e32 v85, v85, v133
	v_add_f32_e32 v86, v86, v134
	v_add_f32_e32 v87, v87, v135
	v_add_f32_e32 v88, v88, v136
	v_add_f32_e32 v89, v89, v137
	v_add_f32_e32 v90, v90, v138
	v_add_f32_e32 v91, v91, v139
	v_add_f32_e32 v92, v92, v140
	v_add_f32_e32 v93, v93, v141
	v_add_f32_e32 v94, v94, v142
	v_add_f32_e32 v95, v95, v143
	s_add_u32 s92, s68, 0x100
	s_addc_u32 s93, s69, 0
	global_store_dword v239, v80, s[92:93]
	s_add_u32 s92, s68, 0x1100
	s_addc_u32 s93, s69, 0
	global_store_dword v239, v81, s[92:93]
	s_add_u32 s92, s68, 0x2100
	s_addc_u32 s93, s69, 0
	global_store_dword v239, v82, s[92:93]
	s_add_u32 s92, s68, 0x3100
	s_addc_u32 s93, s69, 0
	global_store_dword v239, v83, s[92:93]
	s_add_u32 s92, s68, 0x8100
	s_addc_u32 s93, s69, 0
	global_store_dword v239, v84, s[92:93]
	s_add_u32 s92, s68, 0x9100
	s_addc_u32 s93, s69, 0
	global_store_dword v239, v85, s[92:93]
	s_add_u32 s92, s68, 0xa100
	s_addc_u32 s93, s69, 0
	global_store_dword v239, v86, s[92:93]
	s_add_u32 s92, s68, 0xb100
	s_addc_u32 s93, s69, 0
	global_store_dword v239, v87, s[92:93]
	s_add_u32 s92, s68, 0x10100
	s_addc_u32 s93, s69, 0
	global_store_dword v239, v88, s[92:93]
	s_add_u32 s92, s68, 0x11100
	s_addc_u32 s93, s69, 0
	global_store_dword v239, v89, s[92:93]
	s_add_u32 s92, s68, 0x12100
	s_addc_u32 s93, s69, 0
	global_store_dword v239, v90, s[92:93]
	s_add_u32 s92, s68, 0x13100
	s_addc_u32 s93, s69, 0
	global_store_dword v239, v91, s[92:93]
	s_add_u32 s92, s68, 0x18100
	s_addc_u32 s93, s69, 0
	global_store_dword v239, v92, s[92:93]
	s_add_u32 s92, s68, 0x19100
	s_addc_u32 s93, s69, 0
	global_store_dword v239, v93, s[92:93]
	s_add_u32 s92, s68, 0x1a100
	s_addc_u32 s93, s69, 0
	global_store_dword v239, v94, s[92:93]
	s_add_u32 s92, s68, 0x1b100
	s_addc_u32 s93, s69, 0
	global_store_dword v239, v95, s[92:93]
	s_add_u32 s92, s68, 0x20000
	s_addc_u32 s93, s69, 0
	global_load_dword v128, v239, s[92:93]
	s_add_u32 s92, s68, 0x21000
	s_addc_u32 s93, s69, 0
	global_load_dword v129, v239, s[92:93]
	s_add_u32 s92, s68, 0x22000
	s_addc_u32 s93, s69, 0
	global_load_dword v130, v239, s[92:93]
	s_add_u32 s92, s68, 0x23000
	s_addc_u32 s93, s69, 0
	global_load_dword v131, v239, s[92:93]
	s_add_u32 s92, s68, 0x28000
	s_addc_u32 s93, s69, 0
	global_load_dword v132, v239, s[92:93]
	s_add_u32 s92, s68, 0x29000
	s_addc_u32 s93, s69, 0
	global_load_dword v133, v239, s[92:93]
	s_add_u32 s92, s68, 0x2a000
	s_addc_u32 s93, s69, 0
	global_load_dword v134, v239, s[92:93]
	s_add_u32 s92, s68, 0x2b000
	s_addc_u32 s93, s69, 0
	global_load_dword v135, v239, s[92:93]
	s_add_u32 s92, s68, 0x30000
	s_addc_u32 s93, s69, 0
	global_load_dword v136, v239, s[92:93]
	s_add_u32 s92, s68, 0x31000
	s_addc_u32 s93, s69, 0
	global_load_dword v137, v239, s[92:93]
	s_add_u32 s92, s68, 0x32000
	s_addc_u32 s93, s69, 0
	global_load_dword v138, v239, s[92:93]
	s_add_u32 s92, s68, 0x33000
	s_addc_u32 s93, s69, 0
	global_load_dword v139, v239, s[92:93]
	s_add_u32 s92, s68, 0x38000
	s_addc_u32 s93, s69, 0
	global_load_dword v140, v239, s[92:93]
	s_add_u32 s92, s68, 0x39000
	s_addc_u32 s93, s69, 0
	global_load_dword v141, v239, s[92:93]
	s_add_u32 s92, s68, 0x3a000
	s_addc_u32 s93, s69, 0
	global_load_dword v142, v239, s[92:93]
	s_add_u32 s92, s68, 0x3b000
	s_addc_u32 s93, s69, 0
	global_load_dword v143, v239, s[92:93]
	s_waitcnt vmcnt(32)
; DI int crow(int i, int h) { return (i & 3) + 8 * (i >> 2) + 4 * h; }
; template <int NT, class Epi>
; DI void gemm_tile(const u16* __restrict__ A, int lda, const u16* __restrict__ Bt, int ldb, int K, int m0, int n0, const Epi& epi, char* smem) {
;     ...
; #pragma unroll
;   for (int mt = 0; mt < 2; ++mt)
; #pragma unroll
;     for (int nt = 0; nt < NT; ++nt) epi(acc[mt][nt], m0 + wm * 64 + mt * 32, n0 + wn * 32 * NT + nt * 32, lane);
;   DI void operator()(const f32x16& acc, int row0, int col0, int lane) const {
;     const int r = lane & 31, h = lane >> 5, col = col0 + r;
; #pragma unroll
;     for (int i = 0; i < 16; ++i) { float* q = H + (size_t)(row0 + crow(i, h)) * DM + col; *q = *q + acc[i]; }
;   }
	v_add_f32_e32 v64, v64, v240
	v_add_f32_e32 v65, v65, v241
	v_add_f32_e32 v66, v66, v242
	v_add_f32_e32 v67, v67, v243
	v_add_f32_e32 v68, v68, v244
	v_add_f32_e32 v69, v69, v245
	v_add_f32_e32 v70, v70, v246
	v_add_f32_e32 v71, v71, v247
	v_add_f32_e32 v72, v72, v248
	v_add_f32_e32 v73, v73, v249
	v_add_f32_e32 v74, v74, v250
	v_add_f32_e32 v75, v75, v251
	v_add_f32_e32 v76, v76, v252
	v_add_f32_e32 v77, v77, v253
	v_add_f32_e32 v78, v78, v254
	v_add_f32_e32 v79, v79, v255
	s_add_u32 s92, s68, 0x180
	s_addc_u32 s93, s69, 0
	global_store_dword v239, v64, s[92:93]
	s_add_u32 s92, s68, 0x1180
	s_addc_u32 s93, s69, 0
	global_store_dword v239, v65, s[92:93]
	s_add_u32 s92, s68, 0x2180
	s_addc_u32 s93, s69, 0
	global_store_dword v239, v66, s[92:93]
	s_add_u32 s92, s68, 0x3180
	s_addc_u32 s93, s69, 0
	global_store_dword v239, v67, s[92:93]
	s_add_u32 s92, s68, 0x8180
	s_addc_u32 s93, s69, 0
	global_store_dword v239, v68, s[92:93]
	s_add_u32 s92, s68, 0x9180
	s_addc_u32 s93, s69, 0
	global_store_dword v239, v69, s[92:93]
	s_add_u32 s92, s68, 0xa180
	s_addc_u32 s93, s69, 0
	global_store_dword v239, v70, s[92:93]
	s_add_u32 s92, s68, 0xb180
	s_addc_u32 s93, s69, 0
	global_store_dword v239, v71, s[92:93]
	s_add_u32 s92, s68, 0x10180
	s_addc_u32 s93, s69, 0
	global_store_dword v239, v72, s[92:93]
	s_add_u32 s92, s68, 0x11180
	s_addc_u32 s93, s69, 0
	global_store_dword v239, v73, s[92:93]
	s_add_u32 s92, s68, 0x12180
	s_addc_u32 s93, s69, 0
	global_store_dword v239, v74, s[92:93]
	s_add_u32 s92, s68, 0x13180
	s_addc_u32 s93, s69, 0
	global_store_dword v239, v75, s[92:93]
	s_add_u32 s92, s68, 0x18180
	s_addc_u32 s93, s69, 0
	global_store_dword v239, v76, s[92:93]
	s_add_u32 s92, s68, 0x19180
	s_addc_u32 s93, s69, 0
	global_store_dword v239, v77, s[92:93]
	s_add_u32 s92, s68, 0x1a180
	s_addc_u32 s93, s69, 0
	global_store_dword v239, v78, s[92:93]
	s_add_u32 s92, s68, 0x1b180
	s_addc_u32 s93, s69, 0
	global_store_dword v239, v79, s[92:93]
	s_add_u32 s92, s68, 0x20080
	s_addc_u32 s93, s69, 0
	global_load_dword v240, v239, s[92:93]
	s_add_u32 s92, s68, 0x21080
	s_addc_u32 s93, s69, 0
	global_load_dword v241, v239, s[92:93]
	s_add_u32 s92, s68, 0x22080
	s_addc_u32 s93, s69, 0
	global_load_dword v242, v239, s[92:93]
	s_add_u32 s92, s68, 0x23080
	s_addc_u32 s93, s69, 0
	global_load_dword v243, v239, s[92:93]
	s_add_u32 s92, s68, 0x28080
	s_addc_u32 s93, s69, 0
	global_load_dword v244, v239, s[92:93]
	s_add_u32 s92, s68, 0x29080
	s_addc_u32 s93, s69, 0
	global_load_dword v245, v239, s[92:93]
	s_add_u32 s92, s68, 0x2a080
	s_addc_u32 s93, s69, 0
	global_load_dword v246, v239, s[92:93]
	s_add_u32 s92, s68, 0x2b080
	s_addc_u32 s93, s69, 0
	global_load_dword v247, v239, s[92:93]
	s_add_u32 s92, s68, 0x30080
	s_addc_u32 s93, s69, 0
	global_load_dword v248, v239, s[92:93]
	s_add_u32 s92, s68, 0x31080
	s_addc_u32 s93, s69, 0
	global_load_dword v249, v239, s[92:93]
	s_add_u32 s92, s68, 0x32080
	s_addc_u32 s93, s69, 0
	global_load_dword v250, v239, s[92:93]
	s_add_u32 s92, s68, 0x33080
	s_addc_u32 s93, s69, 0
	global_load_dword v251, v239, s[92:93]
	s_add_u32 s92, s68, 0x38080
	s_addc_u32 s93, s69, 0
	global_load_dword v252, v239, s[92:93]
	s_add_u32 s92, s68, 0x39080
	s_addc_u32 s93, s69, 0
	global_load_dword v253, v239, s[92:93]
	s_add_u32 s92, s68, 0x3a080
	s_addc_u32 s93, s69, 0
	global_load_dword v254, v239, s[92:93]
	s_add_u32 s92, s68, 0x3b080
	s_addc_u32 s93, s69, 0
	global_load_dword v255, v239, s[92:93]
	s_waitcnt vmcnt(32)
	v_add_f32_e32 v48, v48, v128
	v_add_f32_e32 v49, v49, v129
	v_add_f32_e32 v50, v50, v130
	v_add_f32_e32 v51, v51, v131
	v_add_f32_e32 v52, v52, v132
	v_add_f32_e32 v53, v53, v133
	v_add_f32_e32 v54, v54, v134
	v_add_f32_e32 v55, v55, v135
	v_add_f32_e32 v56, v56, v136
	v_add_f32_e32 v57, v57, v137
	v_add_f32_e32 v58, v58, v138
	v_add_f32_e32 v59, v59, v139
	v_add_f32_e32 v60, v60, v140
	v_add_f32_e32 v61, v61, v141
	v_add_f32_e32 v62, v62, v142
	v_add_f32_e32 v63, v63, v143
	s_add_u32 s92, s68, 0x20000
	s_addc_u32 s93, s69, 0
	global_store_dword v239, v48, s[92:93]
	s_add_u32 s92, s68, 0x21000
	s_addc_u32 s93, s69, 0
	global_store_dword v239, v49, s[92:93]
	s_add_u32 s92, s68, 0x22000
	s_addc_u32 s93, s69, 0
	global_store_dword v239, v50, s[92:93]
	s_add_u32 s92, s68, 0x23000
	s_addc_u32 s93, s69, 0
	global_store_dword v239, v51, s[92:93]
	s_add_u32 s92, s68, 0x28000
	s_addc_u32 s93, s69, 0
	global_store_dword v239, v52, s[92:93]
	s_add_u32 s92, s68, 0x29000
	s_addc_u32 s93, s69, 0
	global_store_dword v239, v53, s[92:93]
	s_add_u32 s92, s68, 0x2a000
	s_addc_u32 s93, s69, 0
	global_store_dword v239, v54, s[92:93]
	s_add_u32 s92, s68, 0x2b000
	s_addc_u32 s93, s69, 0
	global_store_dword v239, v55, s[92:93]
	s_add_u32 s92, s68, 0x30000
	s_addc_u32 s93, s69, 0
	global_store_dword v239, v56, s[92:93]
	s_add_u32 s92, s68, 0x31000
	s_addc_u32 s93, s69, 0
	global_store_dword v239, v57, s[92:93]
	s_add_u32 s92, s68, 0x32000
	s_addc_u32 s93, s69, 0
	global_store_dword v239, v58, s[92:93]
	s_add_u32 s92, s68, 0x33000
	s_addc_u32 s93, s69, 0
	global_store_dword v239, v59, s[92:93]
	s_add_u32 s92, s68, 0x38000
	s_addc_u32 s93, s69, 0
	global_store_dword v239, v60, s[92:93]
	s_add_u32 s92, s68, 0x39000
	s_addc_u32 s93, s69, 0
	global_store_dword v239, v61, s[92:93]
	s_add_u32 s92, s68, 0x3a000
	s_addc_u32 s93, s69, 0
	global_store_dword v239, v62, s[92:93]
	s_add_u32 s92, s68, 0x3b000
	s_addc_u32 s93, s69, 0
	global_store_dword v239, v63, s[92:93]
	s_add_u32 s92, s68, 0x20100
	s_addc_u32 s93, s69, 0
	global_load_dword v128, v239, s[92:93]
	s_add_u32 s92, s68, 0x21100
	s_addc_u32 s93, s69, 0
	global_load_dword v129, v239, s[92:93]
	s_add_u32 s92, s68, 0x22100
	s_addc_u32 s93, s69, 0
	global_load_dword v130, v239, s[92:93]
	s_add_u32 s92, s68, 0x23100
	s_addc_u32 s93, s69, 0
	global_load_dword v131, v239, s[92:93]
	s_add_u32 s92, s68, 0x28100
	s_addc_u32 s93, s69, 0
	global_load_dword v132, v239, s[92:93]
	s_add_u32 s92, s68, 0x29100
	s_addc_u32 s93, s69, 0
	global_load_dword v133, v239, s[92:93]
	s_add_u32 s92, s68, 0x2a100
	s_addc_u32 s93, s69, 0
	global_load_dword v134, v239, s[92:93]
	s_add_u32 s92, s68, 0x2b100
	s_addc_u32 s93, s69, 0
	global_load_dword v135, v239, s[92:93]
	s_add_u32 s92, s68, 0x30100
	s_addc_u32 s93, s69, 0
	global_load_dword v136, v239, s[92:93]
	s_add_u32 s92, s68, 0x31100
	s_addc_u32 s93, s69, 0
	global_load_dword v137, v239, s[92:93]
	s_add_u32 s92, s68, 0x32100
	s_addc_u32 s93, s69, 0
	global_load_dword v138, v239, s[92:93]
	s_add_u32 s92, s68, 0x33100
	s_addc_u32 s93, s69, 0
	global_load_dword v139, v239, s[92:93]
	s_add_u32 s92, s68, 0x38100
	s_addc_u32 s93, s69, 0
	global_load_dword v140, v239, s[92:93]
	s_add_u32 s92, s68, 0x39100
	s_addc_u32 s93, s69, 0
	global_load_dword v141, v239, s[92:93]
	s_add_u32 s92, s68, 0x3a100
	s_addc_u32 s93, s69, 0
	global_load_dword v142, v239, s[92:93]
	s_add_u32 s92, s68, 0x3b100
	s_addc_u32 s93, s69, 0
	global_load_dword v143, v239, s[92:93]
	s_waitcnt vmcnt(32)
; DI int crow(int i, int h) { return (i & 3) + 8 * (i >> 2) + 4 * h; }
; template <int NT, class Epi>
; DI void gemm_tile(const u16* __restrict__ A, int lda, const u16* __restrict__ Bt, int ldb, int K, int m0, int n0, const Epi& epi, char* smem) {
;     ...
; #pragma unroll
;   for (int mt = 0; mt < 2; ++mt)
; #pragma unroll
;     for (int nt = 0; nt < NT; ++nt) epi(acc[mt][nt], m0 + wm * 64 + mt * 32, n0 + wn * 32 * NT + nt * 32, lane);
;   DI void operator()(const f32x16& acc, int row0, int col0, int lane) const {
;     const int r = lane & 31, h = lane >> 5, col = col0 + r;
; #pragma unroll
;     for (int i = 0; i < 16; ++i) { float* q = H + (size_t)(row0 + crow(i, h)) * DM + col; *q = *q + acc[i]; }
;   }
	v_add_f32_e32 v32, v32, v240
	v_add_f32_e32 v33, v33, v241
	v_add_f32_e32 v34, v34, v242
	v_add_f32_e32 v35, v35, v243
	v_add_f32_e32 v36, v36, v244
	v_add_f32_e32 v37, v37, v245
	v_add_f32_e32 v38, v38, v246
	v_add_f32_e32 v39, v39, v247
	v_add_f32_e32 v40, v40, v248
	v_add_f32_e32 v41, v41, v249
	v_add_f32_e32 v42, v42, v250
	v_add_f32_e32 v43, v43, v251
	v_add_f32_e32 v44, v44, v252
	v_add_f32_e32 v45, v45, v253
	v_add_f32_e32 v46, v46, v254
	v_add_f32_e32 v47, v47, v255
	s_add_u32 s92, s68, 0x20080
	s_addc_u32 s93, s69, 0
	global_store_dword v239, v32, s[92:93]
	s_add_u32 s92, s68, 0x21080
	s_addc_u32 s93, s69, 0
	global_store_dword v239, v33, s[92:93]
	s_add_u32 s92, s68, 0x22080
	s_addc_u32 s93, s69, 0
	global_store_dword v239, v34, s[92:93]
	s_add_u32 s92, s68, 0x23080
	s_addc_u32 s93, s69, 0
	global_store_dword v239, v35, s[92:93]
	s_add_u32 s92, s68, 0x28080
	s_addc_u32 s93, s69, 0
	global_store_dword v239, v36, s[92:93]
	s_add_u32 s92, s68, 0x29080
	s_addc_u32 s93, s69, 0
	global_store_dword v239, v37, s[92:93]
	s_add_u32 s92, s68, 0x2a080
	s_addc_u32 s93, s69, 0
	global_store_dword v239, v38, s[92:93]
	s_add_u32 s92, s68, 0x2b080
	s_addc_u32 s93, s69, 0
	global_store_dword v239, v39, s[92:93]
	s_add_u32 s92, s68, 0x30080
	s_addc_u32 s93, s69, 0
	global_store_dword v239, v40, s[92:93]
	s_add_u32 s92, s68, 0x31080
	s_addc_u32 s93, s69, 0
	global_store_dword v239, v41, s[92:93]
	s_add_u32 s92, s68, 0x32080
	s_addc_u32 s93, s69, 0
	global_store_dword v239, v42, s[92:93]
	s_add_u32 s92, s68, 0x33080
	s_addc_u32 s93, s69, 0
	global_store_dword v239, v43, s[92:93]
	s_add_u32 s92, s68, 0x38080
	s_addc_u32 s93, s69, 0
	global_store_dword v239, v44, s[92:93]
	s_add_u32 s92, s68, 0x39080
	s_addc_u32 s93, s69, 0
	global_store_dword v239, v45, s[92:93]
	s_add_u32 s92, s68, 0x3a080
	s_addc_u32 s93, s69, 0
	global_store_dword v239, v46, s[92:93]
	s_add_u32 s92, s68, 0x3b080
	s_addc_u32 s93, s69, 0
	global_store_dword v239, v47, s[92:93]
	s_add_u32 s92, s68, 0x20180
	s_addc_u32 s93, s69, 0
	global_load_dword v240, v239, s[92:93]
	s_add_u32 s92, s68, 0x21180
	s_addc_u32 s93, s69, 0
	global_load_dword v241, v239, s[92:93]
	s_add_u32 s92, s68, 0x22180
	s_addc_u32 s93, s69, 0
	global_load_dword v242, v239, s[92:93]
	s_add_u32 s92, s68, 0x23180
	s_addc_u32 s93, s69, 0
	global_load_dword v243, v239, s[92:93]
	s_add_u32 s92, s68, 0x28180
	s_addc_u32 s93, s69, 0
	global_load_dword v244, v239, s[92:93]
	s_add_u32 s92, s68, 0x29180
	s_addc_u32 s93, s69, 0
	global_load_dword v245, v239, s[92:93]
	s_add_u32 s92, s68, 0x2a180
	s_addc_u32 s93, s69, 0
	global_load_dword v246, v239, s[92:93]
	s_add_u32 s92, s68, 0x2b180
	s_addc_u32 s93, s69, 0
	global_load_dword v247, v239, s[92:93]
	s_add_u32 s92, s68, 0x30180
	s_addc_u32 s93, s69, 0
	global_load_dword v248, v239, s[92:93]
	s_add_u32 s92, s68, 0x31180
	s_addc_u32 s93, s69, 0
	global_load_dword v249, v239, s[92:93]
	s_add_u32 s92, s68, 0x32180
	s_addc_u32 s93, s69, 0
	global_load_dword v250, v239, s[92:93]
	s_add_u32 s92, s68, 0x33180
	s_addc_u32 s93, s69, 0
	global_load_dword v251, v239, s[92:93]
	s_add_u32 s92, s68, 0x38180
	s_addc_u32 s93, s69, 0
	global_load_dword v252, v239, s[92:93]
	s_add_u32 s92, s68, 0x39180
	s_addc_u32 s93, s69, 0
	global_load_dword v253, v239, s[92:93]
	s_add_u32 s92, s68, 0x3a180
	s_addc_u32 s93, s69, 0
	global_load_dword v254, v239, s[92:93]
	s_add_u32 s92, s68, 0x3b180
	s_addc_u32 s93, s69, 0
	global_load_dword v255, v239, s[92:93]
	s_waitcnt vmcnt(32)
; DI int crow(int i, int h) { return (i & 3) + 8 * (i >> 2) + 4 * h; }
; template <int NT, class Epi>
; DI void gemm_tile(const u16* __restrict__ A, int lda, const u16* __restrict__ Bt, int ldb, int K, int m0, int n0, const Epi& epi, char* smem) {
;     ...
; #pragma unroll
;   for (int mt = 0; mt < 2; ++mt)
; #pragma unroll
;     for (int nt = 0; nt < NT; ++nt) epi(acc[mt][nt], m0 + wm * 64 + mt * 32, n0 + wn * 32 * NT + nt * 32, lane);
;   DI void operator()(const f32x16& acc, int row0, int col0, int lane) const {
;     const int r = lane & 31, h = lane >> 5, col = col0 + r;
; #pragma unroll
;     for (int i = 0; i < 16; ++i) { float* q = H + (size_t)(row0 + crow(i, h)) * DM + col; *q = *q + acc[i]; }
;   }
	v_add_f32_e32 v16, v16, v128
	v_add_f32_e32 v17, v17, v129
	v_add_f32_e32 v18, v18, v130
	v_add_f32_e32 v19, v19, v131
	v_add_f32_e32 v20, v20, v132
	v_add_f32_e32 v21, v21, v133
	v_add_f32_e32 v22, v22, v134
	v_add_f32_e32 v23, v23, v135
	v_add_f32_e32 v24, v24, v136
	v_add_f32_e32 v25, v25, v137
	v_add_f32_e32 v26, v26, v138
	v_add_f32_e32 v27, v27, v139
	v_add_f32_e32 v28, v28, v140
	v_add_f32_e32 v29, v29, v141
	v_add_f32_e32 v30, v30, v142
	v_add_f32_e32 v31, v31, v143
	s_add_u32 s92, s68, 0x20100
	s_addc_u32 s93, s69, 0
	global_store_dword v239, v16, s[92:93]
	s_add_u32 s92, s68, 0x21100
	s_addc_u32 s93, s69, 0
	global_store_dword v239, v17, s[92:93]
	s_add_u32 s92, s68, 0x22100
	s_addc_u32 s93, s69, 0
	global_store_dword v239, v18, s[92:93]
	s_add_u32 s92, s68, 0x23100
	s_addc_u32 s93, s69, 0
	global_store_dword v239, v19, s[92:93]
	s_add_u32 s92, s68, 0x28100
	s_addc_u32 s93, s69, 0
	global_store_dword v239, v20, s[92:93]
	s_add_u32 s92, s68, 0x29100
	s_addc_u32 s93, s69, 0
	global_store_dword v239, v21, s[92:93]
	s_add_u32 s92, s68, 0x2a100
	s_addc_u32 s93, s69, 0
	global_store_dword v239, v22, s[92:93]
	s_add_u32 s92, s68, 0x2b100
	s_addc_u32 s93, s69, 0
	global_store_dword v239, v23, s[92:93]
	s_add_u32 s92, s68, 0x30100
	s_addc_u32 s93, s69, 0
	global_store_dword v239, v24, s[92:93]
	s_add_u32 s92, s68, 0x31100
	s_addc_u32 s93, s69, 0
	global_store_dword v239, v25, s[92:93]
	s_add_u32 s92, s68, 0x32100
	s_addc_u32 s93, s69, 0
	global_store_dword v239, v26, s[92:93]
	s_add_u32 s92, s68, 0x33100
	s_addc_u32 s93, s69, 0
	global_store_dword v239, v27, s[92:93]
	s_add_u32 s92, s68, 0x38100
	s_addc_u32 s93, s69, 0
	global_store_dword v239, v28, s[92:93]
	s_add_u32 s92, s68, 0x39100
	s_addc_u32 s93, s69, 0
	global_store_dword v239, v29, s[92:93]
	s_add_u32 s92, s68, 0x3a100
	s_addc_u32 s93, s69, 0
	global_store_dword v239, v30, s[92:93]
	s_add_u32 s92, s68, 0x3b100
	s_addc_u32 s93, s69, 0
	global_store_dword v239, v31, s[92:93]
	s_waitcnt vmcnt(16)
	v_add_f32_e32 v0, v0, v240
	v_add_f32_e32 v1, v1, v241
	v_add_f32_e32 v2, v2, v242
	v_add_f32_e32 v3, v3, v243
	v_add_f32_e32 v4, v4, v244
	v_add_f32_e32 v5, v5, v245
	v_add_f32_e32 v6, v6, v246
	v_add_f32_e32 v7, v7, v247
	v_add_f32_e32 v8, v8, v248
	v_add_f32_e32 v9, v9, v249
	v_add_f32_e32 v10, v10, v250
	v_add_f32_e32 v11, v11, v251
	v_add_f32_e32 v12, v12, v252
	v_add_f32_e32 v13, v13, v253
	v_add_f32_e32 v14, v14, v254
	v_add_f32_e32 v15, v15, v255
	s_add_u32 s92, s68, 0x20180
	s_addc_u32 s93, s69, 0
	global_store_dword v239, v0, s[92:93]
	s_add_u32 s92, s68, 0x21180
	s_addc_u32 s93, s69, 0
	global_store_dword v239, v1, s[92:93]
	s_add_u32 s92, s68, 0x22180
	s_addc_u32 s93, s69, 0
	global_store_dword v239, v2, s[92:93]
	s_add_u32 s92, s68, 0x23180
	s_addc_u32 s93, s69, 0
	global_store_dword v239, v3, s[92:93]
	s_add_u32 s92, s68, 0x28180
	s_addc_u32 s93, s69, 0
	global_store_dword v239, v4, s[92:93]
	s_add_u32 s92, s68, 0x29180
	s_addc_u32 s93, s69, 0
	global_store_dword v239, v5, s[92:93]
	s_add_u32 s92, s68, 0x2a180
	s_addc_u32 s93, s69, 0
	global_store_dword v239, v6, s[92:93]
	s_add_u32 s92, s68, 0x2b180
	s_addc_u32 s93, s69, 0
	global_store_dword v239, v7, s[92:93]
	s_add_u32 s92, s68, 0x30180
	s_addc_u32 s93, s69, 0
	global_store_dword v239, v8, s[92:93]
	s_add_u32 s92, s68, 0x31180
	s_addc_u32 s93, s69, 0
	global_store_dword v239, v9, s[92:93]
	s_add_u32 s92, s68, 0x32180
	s_addc_u32 s93, s69, 0
	global_store_dword v239, v10, s[92:93]
	s_add_u32 s92, s68, 0x33180
	s_addc_u32 s93, s69, 0
	global_store_dword v239, v11, s[92:93]
	s_add_u32 s92, s68, 0x38180
	s_addc_u32 s93, s69, 0
	global_store_dword v239, v12, s[92:93]
	s_add_u32 s92, s68, 0x39180
	s_addc_u32 s93, s69, 0
	global_store_dword v239, v13, s[92:93]
	s_add_u32 s92, s68, 0x3a180
	s_addc_u32 s93, s69, 0
	global_store_dword v239, v14, s[92:93]
	s_add_u32 s92, s68, 0x3b180
	s_addc_u32 s93, s69, 0
	global_store_dword v239, v15, s[92:93]
	s_cmp_lg_u32 s91, 0
	s_cbranch_scc1 .LBB0_642
